# LRU gate chain peephole: bias-add+scale folded into v_fmamk, k8*log2e prescaled, max-before-sqrt replaced by abs modifier (f32 math unchanged)
# speedup vs baseline: 1.0118x; 1.0118x over previous
.LBB0_343:
	s_or_b64 exec, exec, s[42:43]
	v_mul_f32_e32 v8, 0xbfb8aa3b, v8
	v_exp_f32_e32 v10, v8
	s_mov_b32 s5, 0x3f2aaaab
	s_mov_b32 s6, 0x3f317218
	s_mov_b32 s7, 0x7f800000
	v_add_f32_e32 v11, 1.0, v10
	v_frexp_mant_f32_e32 v13, v11
	v_cvt_f64_f32_e32 v[8:9], v11
	v_add_f32_e32 v12, -1.0, v11
	v_frexp_exp_i32_f64_e32 v8, v[8:9]
	v_cmp_gt_f32_e32 vcc, s5, v13
	v_sub_f32_e32 v14, v12, v11
	v_sub_f32_e32 v12, v10, v12
	v_subbrev_co_u32_e32 v8, vcc, 0, v8, vcc
	v_add_f32_e32 v14, 1.0, v14
	v_sub_u32_e32 v9, 0, v8
	v_add_f32_e32 v12, v12, v14
	v_ldexp_f32 v11, v11, v9
	v_ldexp_f32 v9, v12, v9
	v_add_f32_e32 v12, -1.0, v11
	v_add_f32_e32 v15, 1.0, v11
	v_add_f32_e32 v13, 1.0, v12
	v_add_f32_e32 v16, -1.0, v15
	v_sub_f32_e32 v13, v11, v13
	v_sub_f32_e32 v11, v11, v16
	v_add_f32_e32 v13, v9, v13
	v_add_f32_e32 v9, v9, v11
	v_add_f32_e32 v11, v15, v9
	v_rcp_f32_e32 v16, v11
	v_add_f32_e32 v14, v12, v13
	v_sub_f32_e32 v12, v14, v12
	v_sub_f32_e32 v12, v13, v12
	v_sub_f32_e32 v13, v11, v15
	v_sub_f32_e32 v9, v9, v13
	v_mul_f32_e32 v13, v14, v16
	v_mul_f32_e32 v15, v11, v13
	v_fma_f32 v17, v13, v11, -v15
	v_fmac_f32_e32 v17, v13, v9
	v_add_f32_e32 v18, v15, v17
	v_sub_f32_e32 v19, v14, v18
	v_sub_f32_e32 v14, v14, v19
	v_sub_f32_e32 v15, v18, v15
	v_sub_f32_e32 v14, v14, v18
	v_add_f32_e32 v12, v12, v14
	v_sub_f32_e32 v14, v15, v17
	v_add_f32_e32 v12, v14, v12
	v_add_f32_e32 v14, v19, v12
	v_mul_f32_e32 v15, v16, v14
	v_mul_f32_e32 v17, v11, v15
	v_fma_f32 v11, v15, v11, -v17
	v_fmac_f32_e32 v11, v15, v9
	v_sub_f32_e32 v9, v19, v14
	v_add_f32_e32 v9, v12, v9
	v_add_f32_e32 v12, v17, v11
	v_sub_f32_e32 v18, v14, v12
	v_sub_f32_e32 v14, v14, v18
	v_sub_f32_e32 v17, v12, v17
	v_sub_f32_e32 v12, v14, v12
	v_add_f32_e32 v9, v9, v12
	v_sub_f32_e32 v11, v17, v11
	v_cvt_f32_i32_e32 v8, v8
	v_add_f32_e32 v9, v11, v9
	v_add_f32_e32 v11, v13, v15
	v_add_f32_e32 v9, v18, v9
	v_sub_f32_e32 v12, v11, v13
	v_mul_f32_e32 v9, v16, v9
	v_sub_f32_e32 v12, v15, v12
	v_add_f32_e32 v9, v12, v9
	v_mul_f32_e32 v15, 0x3f317218, v8
	v_add_f32_e32 v12, v11, v9
	v_fma_f32 v16, v8, s6, -v15
	v_mul_f32_e32 v13, v12, v12
	v_fmac_f32_e32 v16, 0xb102e308, v8
	v_sub_f32_e32 v8, v12, v11
	v_fmamk_f32 v14, v13, 0x3e9b6dac, v179
	v_sub_f32_e32 v8, v9, v8
	v_add_f32_e32 v9, v15, v16
	v_fmaak_f32 v14, v13, v14, 0x3f2aaada
	v_sub_f32_e32 v11, v9, v15
	v_ldexp_f32 v15, v12, 1
	v_mul_f32_e32 v12, v12, v13
	v_mul_f32_e32 v12, v12, v14
	v_add_f32_e32 v13, v15, v12
	v_sub_f32_e32 v14, v13, v15
	v_ldexp_f32 v8, v8, 1
	v_sub_f32_e32 v12, v12, v14
	v_add_f32_e32 v8, v8, v12
	v_add_f32_e32 v12, v13, v8
	v_sub_f32_e32 v13, v12, v13
	v_sub_f32_e32 v8, v8, v13
	v_add_f32_e32 v13, v9, v12
	v_sub_f32_e32 v14, v13, v9
	v_sub_f32_e32 v15, v13, v14
	v_sub_f32_e32 v11, v16, v11
	v_sub_f32_e32 v9, v9, v15
	v_sub_f32_e32 v12, v12, v14
	v_add_f32_e32 v9, v12, v9
	v_add_f32_e32 v12, v11, v8
	v_sub_f32_e32 v14, v12, v11
	v_sub_f32_e32 v15, v12, v14
	v_sub_f32_e32 v11, v11, v15
	v_sub_f32_e32 v8, v8, v14
	v_add_f32_e32 v9, v12, v9
	v_add_f32_e32 v8, v8, v11
	v_add_f32_e32 v11, v13, v9
	v_sub_f32_e32 v12, v11, v13
	v_sub_f32_e32 v9, v9, v12
	v_add_f32_e32 v8, v8, v9
	v_mul_f32_e32 v7, 0xbfb8aa3b, v7
	v_add_f32_e32 v8, v11, v8
	v_cmp_neq_f32_e32 vcc, s7, v10
	v_exp_f32_e32 v7, v7
	s_mov_b32 s8, 0x33800000
	v_cndmask_b32_e32 v8, v182, v8, vcc
	v_cmp_ngt_f32_e32 vcc, -1.0, v10
	v_lshl_add_u64 v[64:65], s[44:45], 0, v[144:145]
	v_cmp_gt_u32_e64 s[42:43], 32, v5
	v_cndmask_b32_e32 v8, v183, v8, vcc
	v_cmp_neq_f32_e32 vcc, -1.0, v10
	s_mov_b32 s4, 0
	v_add_u32_e32 v100, -2, v6
	v_cndmask_b32_e32 v8, v184, v8, vcc
	v_cmp_lt_f32_e64 vcc, |v10|, s8
	s_waitcnt lgkmcnt(0)
	s_barrier
	v_cndmask_b32_e32 v8, v8, v10, vcc
	v_add_f32_e32 v10, 1.0, v7
	v_mul_f32_e32 v92, 0xc1000000, v8
	v_add_f32_e32 v8, -1.0, v10
	v_sub_f32_e32 v9, v8, v10
	v_add_f32_e32 v9, 1.0, v9
	v_sub_f32_e32 v8, v7, v8
	v_add_f32_e32 v11, v8, v9
	v_frexp_mant_f32_e32 v12, v10
	v_cvt_f64_f32_e32 v[8:9], v10
	v_frexp_exp_i32_f64_e32 v8, v[8:9]
	v_cmp_gt_f32_e32 vcc, s5, v12
	v_readlane_b32 s5, v242, 3
	s_nop 0
	v_subbrev_co_u32_e32 v8, vcc, 0, v8, vcc
	v_sub_u32_e32 v9, 0, v8
	v_ldexp_f32 v10, v10, v9
	v_ldexp_f32 v9, v11, v9
	v_add_f32_e32 v11, -1.0, v10
	v_add_f32_e32 v14, 1.0, v10
	v_add_f32_e32 v12, 1.0, v11
	v_add_f32_e32 v15, -1.0, v14
	v_sub_f32_e32 v12, v10, v12
	v_sub_f32_e32 v10, v10, v15
	v_add_f32_e32 v12, v9, v12
	v_add_f32_e32 v9, v9, v10
	v_add_f32_e32 v10, v14, v9
	v_rcp_f32_e32 v15, v10
	v_add_f32_e32 v13, v11, v12
	v_sub_f32_e32 v11, v13, v11
	v_sub_f32_e32 v11, v12, v11
	v_sub_f32_e32 v12, v10, v14
	v_sub_f32_e32 v9, v9, v12
	v_mul_f32_e32 v12, v13, v15
	v_mul_f32_e32 v14, v10, v12
	v_fma_f32 v16, v12, v10, -v14
	v_fmac_f32_e32 v16, v12, v9
	v_add_f32_e32 v17, v14, v16
	v_sub_f32_e32 v18, v13, v17
	v_sub_f32_e32 v13, v13, v18
	v_sub_f32_e32 v14, v17, v14
	v_sub_f32_e32 v13, v13, v17
	v_add_f32_e32 v11, v11, v13
	v_sub_f32_e32 v13, v14, v16
	v_add_f32_e32 v11, v13, v11
	v_add_f32_e32 v13, v18, v11
	v_mul_f32_e32 v14, v15, v13
	v_mul_f32_e32 v16, v10, v14
	v_fma_f32 v10, v14, v10, -v16
	v_fmac_f32_e32 v10, v14, v9
	v_sub_f32_e32 v9, v18, v13
	v_add_f32_e32 v9, v11, v9
	v_add_f32_e32 v11, v16, v10
	v_sub_f32_e32 v17, v13, v11
	v_sub_f32_e32 v13, v13, v17
	v_sub_f32_e32 v16, v11, v16
	v_sub_f32_e32 v11, v13, v11
	v_add_f32_e32 v9, v9, v11
	v_sub_f32_e32 v10, v16, v10
	v_cvt_f32_i32_e32 v8, v8
	v_add_f32_e32 v9, v10, v9
	v_add_f32_e32 v10, v12, v14
	v_add_f32_e32 v9, v17, v9
	v_sub_f32_e32 v11, v10, v12
	v_mul_f32_e32 v9, v15, v9
	v_sub_f32_e32 v11, v14, v11
	v_add_f32_e32 v9, v11, v9
	v_mul_f32_e32 v14, 0x3f317218, v8
	v_add_f32_e32 v11, v10, v9
	v_fma_f32 v15, v8, s6, -v14
	v_mul_f32_e32 v12, v11, v11
	v_fmac_f32_e32 v15, 0xb102e308, v8
	v_sub_f32_e32 v8, v11, v10
	v_fmamk_f32 v13, v12, 0x3e9b6dac, v179
	v_sub_f32_e32 v8, v9, v8
	v_add_f32_e32 v9, v14, v15
	v_fmaak_f32 v13, v12, v13, 0x3f2aaada
	v_sub_f32_e32 v10, v9, v14
	v_ldexp_f32 v14, v11, 1
	v_mul_f32_e32 v11, v11, v12
	v_mul_f32_e32 v11, v11, v13
	v_add_f32_e32 v12, v14, v11
	v_sub_f32_e32 v13, v12, v14
	v_ldexp_f32 v8, v8, 1
	v_sub_f32_e32 v11, v11, v13
	v_add_f32_e32 v8, v8, v11
	v_add_f32_e32 v11, v12, v8
	v_sub_f32_e32 v12, v11, v12
	v_sub_f32_e32 v8, v8, v12
	v_add_f32_e32 v12, v9, v11
	v_sub_f32_e32 v13, v12, v9
	v_sub_f32_e32 v14, v12, v13
	v_sub_f32_e32 v10, v15, v10
	v_sub_f32_e32 v9, v9, v14
	v_sub_f32_e32 v11, v11, v13
	v_add_f32_e32 v9, v11, v9
	v_add_f32_e32 v11, v10, v8
	v_sub_f32_e32 v13, v11, v10
	v_sub_f32_e32 v14, v11, v13
	v_sub_f32_e32 v10, v10, v14
	v_sub_f32_e32 v8, v8, v13
	v_add_f32_e32 v9, v11, v9
	v_add_f32_e32 v8, v8, v10
	v_add_f32_e32 v10, v12, v9
	v_sub_f32_e32 v11, v10, v12
	v_sub_f32_e32 v9, v9, v11
	v_add_f32_e32 v8, v8, v9
	v_add_f32_e32 v8, v10, v8
	v_lshlrev_b32_e32 v10, 2, v0
	v_and_b32_e32 v10, 60, v10
	v_lshlrev_b32_e32 v11, 2, v10
	v_cmp_neq_f32_e32 vcc, s7, v7
	v_add_u32_e32 v94, 0, v11
	v_lshlrev_b32_e32 v10, 1, v10
	v_readlane_b32 s7, v242, 4
	v_sub_u32_e32 v95, v94, v10
	s_movk_i32 s6, 0x90
	v_add_u32_e32 v96, s7, v10
	v_and_b32_e32 v10, 0xffffffe0, v88
	v_or_b32_e32 v4, v10, v4
	v_cndmask_b32_e32 v8, v182, v8, vcc
	v_cmp_ngt_f32_e32 vcc, -1.0, v7
	v_mul_lo_u32 v4, v4, s6
	v_lshlrev_b32_e32 v14, 12, v1
	v_and_b32_e32 v1, 0x1fffff80, v0
	v_cndmask_b32_e32 v8, v183, v8, vcc
	v_cmp_neq_f32_e32 vcc, -1.0, v7
	v_lshlrev_b32_e32 v9, 3, v3
	v_add_u32_e32 v4, s7, v4
	v_lshlrev_b32_e32 v1, 3, v1
	v_readlane_b32 s7, v242, 2
	v_cndmask_b32_e32 v8, v184, v8, vcc
	v_cmp_lt_f32_e64 vcc, |v7|, s8
	v_add3_u32 v97, s7, v9, v1
	v_and_b32_e32 v1, 0x1fffffc0, v0
	v_cndmask_b32_e32 v7, v8, v7, vcc
	v_lshlrev_b32_e32 v8, 3, v5
	v_add_u32_e32 v11, s5, v11
	v_lshl_add_u32 v3, v3, 2, s5
	s_movk_i32 s5, 0x80
	v_lshlrev_b32_e32 v1, 3, v1
	v_mul_f32_e32 v93, 0xc1000000, v7
	v_lshrrev_b32_e32 v7, 5, v5
	v_and_b32_e32 v12, -4, v88
	v_lshl_add_u32 v15, v5, 4, 0
	v_cmp_gt_i32_e64 s[44:45], s5, v0
	v_add3_u32 v5, s7, v8, v1
	v_or_b32_e32 v1, 3, v88
	s_movk_i32 s5, 0x110
	v_mul_lo_u32 v98, v12, s6
	v_mul_lo_u32 v99, v1, s6
	v_mul_lo_u32 v9, v12, s5
	v_mul_lo_u32 v12, v1, s5
	v_lshl_or_b32 v1, v7, 2, v10
	v_lshlrev_b32_e32 v13, 4, v7
	v_mul_lo_u32 v7, v1, s5
	v_readlane_b32 s5, v243, 55
	s_add_u32 s0, s0, s5
	v_readlane_b32 s5, v243, 56
	s_addc_u32 s1, s1, s5
	s_mov_b32 s5, 0x104000
	v_cmp_gt_u32_e32 vcc, 64, v0
	v_mad_i64_i32 v[0:1], s[6:7], v2, s5, 0
	v_or_b32_e32 v0, v0, v8
	v_cndmask_b32_e64 v10, v185, 0, vcc
	v_cndmask_b32_e32 v16, v186, v187, vcc
	v_cndmask_b32_e32 v17, v187, v186, vcc
	v_cndmask_b32_e32 v18, 0, v185, vcc
	v_lshl_add_u64 v[66:67], s[0:1], 0, v[0:1]
	v_readlane_b32 s0, v243, 57
	v_add_u32_e32 v101, v11, v9
	v_add_u32_e32 v102, v11, v12
	v_add_u32_e32 v103, v4, v13
	v_add_u32_e32 v104, v3, v7
	v_add_u32_e32 v105, v5, v10
	v_add_u32_e32 v106, v5, v16
	v_add_u32_e32 v107, v5, v17
	v_add_u32_e32 v108, v5, v18
	v_add_u32_e32 v109, v15, v14
	v_readlane_b32 s5, v243, 60
	s_mov_b32 s6, s0
	v_readlane_b32 s1, v243, 58
	v_mul_f32_e32 v84, 0xbfb8aa3b, v84
	v_mul_f32_e32 v85, 0xbfb8aa3b, v85
	v_mul_f32_e32 v86, 0xbfb8aa3b, v86
	v_mul_f32_e32 v87, 0xbfb8aa3b, v87
	v_mul_f32_e32 v92, 0x3fb8aa3b, v92
	v_mul_f32_e32 v93, 0x3fb8aa3b, v93
	s_branch .LBB0_345

.LBB0_351:
	s_mul_i32 s7, s4, 0x4a40
	v_add_u32_e32 v52, s7, v95
	v_add_u32_e32 v4, v52, v98
	v_add_u32_e32 v58, 0x8800, v4
	ds_read_b128 v[0:3], v94 offset:32768
	ds_read2_b64 v[4:7], v58 offset1:18
	ds_read_b128 v[8:11], v94 offset:33024
	ds_read_b128 v[12:15], v94 offset:33280
	ds_read_b128 v[16:19], v94 offset:33536
	ds_read_b128 v[20:23], v94 offset:33792
	s_waitcnt lgkmcnt(4)
	v_lshlrev_b32_e32 v28, 16, v4
	v_and_b32_e32 v29, 0xffff0000, v4
	v_add_u32_e32 v4, v52, v99
	v_lshlrev_b32_e32 v30, 16, v5
	v_and_b32_e32 v31, 0xffff0000, v5
	ds_read_b64 v[4:5], v4 offset:34816
	v_lshlrev_b32_e32 v48, 16, v6
	v_and_b32_e32 v49, 0xffff0000, v6
	v_lshlrev_b32_e32 v50, 16, v7
	v_and_b32_e32 v51, 0xffff0000, v7
	s_waitcnt lgkmcnt(0)
	v_lshlrev_b32_e32 v54, 16, v4
	v_and_b32_e32 v55, 0xffff0000, v4
	v_lshlrev_b32_e32 v56, 16, v5
	v_and_b32_e32 v57, 0xffff0000, v5
	ds_read2_b64 v[4:7], v58 offset0:90 offset1:108
	ds_read2_b64 v[24:27], v58 offset0:36 offset1:72
	v_add_u32_e32 v72, 0x800, v104
	v_and_b32_e32 v114, 64, v180
	v_xor_b32_e32 v116, 32, v180
	s_waitcnt lgkmcnt(1)
	v_lshlrev_b32_e32 v60, 16, v4
	v_and_b32_e32 v61, 0xffff0000, v4
	v_lshlrev_b32_e32 v62, 16, v5
	v_and_b32_e32 v63, 0xffff0000, v5
	v_lshlrev_b32_e32 v68, 16, v6
	v_and_b32_e32 v69, 0xffff0000, v6
	v_lshlrev_b32_e32 v70, 16, v7
	v_and_b32_e32 v71, 0xffff0000, v7
	v_pk_fma_f32 v[4:5], v[0:1], v[28:29], v[20:21]
	v_pk_fma_f32 v[6:7], v[2:3], v[30:31], v[22:23]
	s_waitcnt lgkmcnt(0)
	v_lshlrev_b32_e32 v52, 16, v24
	v_and_b32_e32 v53, 0xffff0000, v24
	v_lshlrev_b32_e32 v24, 16, v25
	v_and_b32_e32 v25, 0xffff0000, v25
	v_pk_fma_f32 v[6:7], v[10:11], v[50:51], v[6:7]
	v_pk_fma_f32 v[4:5], v[8:9], v[48:49], v[4:5]
	v_pk_fma_f32 v[6:7], v[14:15], v[24:25], v[6:7]
	v_pk_fma_f32 v[4:5], v[12:13], v[52:53], v[4:5]
	v_pk_fma_f32 v[6:7], v[18:19], v[56:57], v[6:7]
	v_pk_fma_f32 v[4:5], v[16:17], v[54:55], v[4:5]
	ds_write_b128 v101, v[4:7]
	v_cvt_pk_bf16_f32 v4, v4, v5
	v_cvt_pk_bf16_f32 v5, v6, v7
	v_add_u32_e32 v28, v96, v98
	ds_write_b64 v28, v[4:5]
	v_pk_fma_f32 v[4:5], v[0:1], v[48:49], v[20:21]
	v_pk_fma_f32 v[6:7], v[2:3], v[50:51], v[22:23]
	v_pk_fma_f32 v[4:5], v[8:9], v[52:53], v[4:5]
	v_pk_fma_f32 v[6:7], v[10:11], v[24:25], v[6:7]
	v_lshlrev_b32_e32 v58, 16, v26
	v_and_b32_e32 v59, 0xffff0000, v26
	v_lshlrev_b32_e32 v26, 16, v27
	v_and_b32_e32 v27, 0xffff0000, v27
	v_pk_fma_f32 v[4:5], v[12:13], v[54:55], v[4:5]
	v_pk_fma_f32 v[6:7], v[14:15], v[56:57], v[6:7]
	v_pk_fma_f32 v[4:5], v[16:17], v[58:59], v[4:5]
	v_pk_fma_f32 v[6:7], v[18:19], v[26:27], v[6:7]
	ds_write_b128 v101, v[4:7] offset:272
	v_cvt_pk_bf16_f32 v4, v4, v5
	v_cvt_pk_bf16_f32 v5, v6, v7
	ds_write_b64 v28, v[4:5] offset:144
	v_pk_fma_f32 v[4:5], v[0:1], v[52:53], v[20:21]
	v_pk_fma_f32 v[6:7], v[2:3], v[24:25], v[22:23]
	v_pk_fma_f32 v[0:1], v[0:1], v[54:55], v[20:21]
	v_pk_fma_f32 v[2:3], v[2:3], v[56:57], v[22:23]
	v_pk_fma_f32 v[6:7], v[10:11], v[56:57], v[6:7]
	v_pk_fma_f32 v[4:5], v[8:9], v[54:55], v[4:5]
	v_pk_fma_f32 v[2:3], v[10:11], v[26:27], v[2:3]
	v_pk_fma_f32 v[0:1], v[8:9], v[58:59], v[0:1]
	v_pk_fma_f32 v[4:5], v[12:13], v[58:59], v[4:5]
	v_pk_fma_f32 v[6:7], v[14:15], v[26:27], v[6:7]
	v_pk_fma_f32 v[0:1], v[12:13], v[60:61], v[0:1]
	v_pk_fma_f32 v[2:3], v[14:15], v[62:63], v[2:3]
	v_pk_fma_f32 v[6:7], v[18:19], v[62:63], v[6:7]
	v_pk_fma_f32 v[4:5], v[16:17], v[60:61], v[4:5]
	v_pk_fma_f32 v[2:3], v[18:19], v[70:71], v[2:3]
	v_pk_fma_f32 v[0:1], v[16:17], v[68:69], v[0:1]
	ds_write_b128 v101, v[4:7] offset:544
	v_cvt_pk_bf16_f32 v4, v4, v5
	v_cvt_pk_bf16_f32 v5, v6, v7
	ds_write_b64 v28, v[4:5] offset:288
	ds_write_b128 v102, v[0:3]
	v_cvt_pk_bf16_f32 v0, v0, v1
	v_cvt_pk_bf16_f32 v1, v2, v3
	v_add_u32_e32 v2, v96, v99
	ds_write_b64 v2, v[0:1]
	s_waitcnt lgkmcnt(0)
	s_barrier
	ds_read_b128 v[48:51], v103
	ds_read_b128 v[0:3], v109
	s_waitcnt lgkmcnt(0)
	v_mfma_f32_32x32x16_bf16 v[16:31], v[48:51], v[0:3], 0
	ds_read_b128 v[0:3], v109 offset:8192
	ds_read_b128 v[56:59], v103 offset:32
	ds_read_b128 v[52:55], v109 offset:1024
	v_add_u32_e32 v78, 0x1a00, v104
	s_waitcnt lgkmcnt(2)
	v_mfma_f32_32x32x16_bf16 v[0:15], v[48:51], v[0:3], 0
	s_waitcnt lgkmcnt(0)
	v_mfma_f32_32x32x16_bf16 v[16:31], v[56:59], v[52:55], v[16:31]
	ds_read_b128 v[52:55], v109 offset:9216
	s_waitcnt lgkmcnt(0)
	v_mfma_f32_32x32x16_bf16 v[0:15], v[56:59], v[52:55], v[0:15]
	ds_read_b128 v[60:63], v103 offset:64
	ds_read_b128 v[68:71], v109 offset:2048
	ds_read_b128 v[52:55], v103 offset:96
	ds_read2_b32 v[76:77], v104 offset1:68
	ds_read2_b32 v[80:81], v104 offset0:136 offset1:204
	ds_read2_b32 v[74:75], v72 offset0:32 offset1:100
	ds_read2_b32 v[82:83], v72 offset0:168 offset1:236
	ds_read_b128 v[110:113], v109 offset:10240
	s_waitcnt lgkmcnt(6)
	v_mfma_f32_32x32x16_bf16 v[16:31], v[60:63], v[68:71], v[16:31]
	v_add_u32_e32 v68, 0x1000, v104
	ds_read2_b32 v[70:71], v68 offset0:64 offset1:132
	v_add_u32_e32 v68, 0x1200, v104
	ds_read2_b32 v[72:73], v68 offset0:72 offset1:140
	v_add_u32_e32 v68, 0x1800, v104
	s_waitcnt lgkmcnt(2)
	v_mfma_f32_32x32x16_bf16 v[0:15], v[60:63], v[110:113], v[0:15]
	ds_read2_b32 v[68:69], v68 offset0:96 offset1:164
	ds_read_b128 v[110:113], v109 offset:3072
	ds_read2_b32 v[78:79], v78 offset0:104 offset1:172
	s_waitcnt lgkmcnt(1)
	v_mfma_f32_32x32x16_bf16 v[16:31], v[52:55], v[110:113], v[16:31]
	v_add_u32_e32 v110, 64, v114
	ds_read_b128 v[112:115], v109 offset:11264
	v_cmp_lt_i32_e32 vcc, v116, v110
	s_nop 1
	v_cndmask_b32_e32 v110, v180, v116, vcc
	v_lshlrev_b32_e32 v110, 2, v110
	s_nop 4
	v_fmamk_f32 v17, v17, 0xbfb8aa3b, v84
	v_exp_f32_e32 v17, v17
	v_fmamk_f32 v18, v18, 0xbfb8aa3b, v84
	v_exp_f32_e32 v18, v18
	v_add_f32_e32 v17, 1.0, v17
	v_rcp_f32_e32 v17, v17
	v_fmamk_f32 v19, v19, 0xbfb8aa3b, v84
	v_add_f32_e32 v18, 1.0, v18
	v_rcp_f32_e32 v111, v18
	v_mul_f32_e32 v17, v92, v17
	v_fmamk_f32 v20, v20, 0xbfb8aa3b, v84
	s_waitcnt lgkmcnt(0)
	v_mfma_f32_32x32x16_bf16 v[0:15], v[52:55], v[112:115], v[0:15]
	v_exp_f32_e32 v18, v17
	v_mul_f32_e32 v17, v92, v111
	v_exp_f32_e32 v19, v19
	v_exp_f32_e32 v111, v20
	v_exp_f32_e32 v20, v17
	v_add_f32_e32 v17, 1.0, v19
	v_add_f32_e32 v19, 1.0, v111
	v_rcp_f32_e32 v19, v19
	s_nop 2
	s_nop 0
	v_fmamk_f32 v4, v4, 0xbfb8aa3b, v85
	v_exp_f32_e32 v4, v4
	v_mul_f32_e32 v19, v92, v19
	v_exp_f32_e32 v111, v19
	v_add_f32_e32 v4, 1.0, v4
	v_rcp_f32_e32 v19, v4
	v_rcp_f32_e32 v17, v17
	v_fma_f32 v4, -v111, v111, 1.0
	v_sqrt_f32_e64 v112, |v4|
	v_mul_f32_e32 v4, v92, v17
	v_fmamk_f32 v5, v5, 0xbfb8aa3b, v85
	v_mul_f32_e32 v17, v19, v112
	v_fmamk_f32 v19, v21, 0xbfb8aa3b, v84
	v_exp_f32_e32 v19, v19
	v_exp_f32_e32 v5, v5
	v_fmamk_f32 v7, v7, 0xbfb8aa3b, v85
	v_add_f32_e32 v19, 1.0, v19
	v_rcp_f32_e32 v19, v19
	v_add_f32_e32 v5, 1.0, v5
	v_rcp_f32_e32 v5, v5
	v_exp_f32_e32 v7, v7
	v_mul_f32_e32 v19, v92, v19
	v_exp_f32_e32 v114, v19
	v_fmamk_f32 v19, v22, 0xbfb8aa3b, v84
	v_exp_f32_e32 v19, v19
	v_fma_f32 v21, -v114, v114, 1.0
	v_sqrt_f32_e64 v21, |v21|
	v_add_f32_e32 v19, 1.0, v19
	v_rcp_f32_e32 v19, v19
	v_fmamk_f32 v8, v8, 0xbfb8aa3b, v85
	v_mul_f32_e32 v5, v5, v21
	v_fmamk_f32 v21, v23, 0xbfb8aa3b, v84
	v_exp_f32_e32 v21, v21
	v_add_f32_e32 v7, 1.0, v7
	v_mul_f32_e32 v19, v92, v19
	v_add_f32_e32 v21, 1.0, v21
	v_rcp_f32_e32 v21, v21
	v_rcp_f32_e32 v7, v7
	v_exp_f32_e32 v8, v8
	v_fmamk_f32 v6, v6, 0xbfb8aa3b, v85
	v_mul_f32_e32 v21, v92, v21
	v_exp_f32_e32 v116, v21
	v_fmamk_f32 v21, v24, 0xbfb8aa3b, v84
	v_fma_f32 v22, -v116, v116, 1.0
	v_sqrt_f32_e64 v22, |v22|
	v_exp_f32_e32 v115, v19
	v_exp_f32_e32 v6, v6
	v_exp_f32_e32 v21, v21
	v_mul_f32_e32 v118, v7, v22
	v_add_f32_e32 v7, 1.0, v8
	v_fmamk_f32 v8, v25, 0xbfb8aa3b, v84
	v_fma_f32 v19, -v115, v115, 1.0
	v_exp_f32_e32 v8, v8
	v_add_f32_e32 v6, 1.0, v6
	v_add_f32_e32 v21, 1.0, v21
	v_rcp_f32_e32 v6, v6
	v_sqrt_f32_e64 v19, |v19|
	v_rcp_f32_e32 v21, v21
	v_add_f32_e32 v8, 1.0, v8
	v_rcp_f32_e32 v8, v8
	v_mul_f32_e32 v117, v6, v19
	v_mul_f32_e32 v6, v92, v21
	v_exp_f32_e32 v6, v6
	v_fmamk_f32 v9, v9, 0xbfb8aa3b, v85
	v_mul_f32_e32 v8, v92, v8
	v_exp_f32_e32 v9, v9
	v_exp_f32_e32 v8, v8
	v_rcp_f32_e32 v23, v7
	v_fma_f32 v7, -v6, v6, 1.0
	v_sqrt_f32_e64 v25, |v7|
	v_add_f32_e32 v7, 1.0, v9
	v_rcp_f32_e32 v22, v7
	v_fma_f32 v7, -v8, v8, 1.0
	v_sqrt_f32_e64 v24, |v7|
	v_fmamk_f32 v7, v26, 0xbfb8aa3b, v84
	v_exp_f32_e32 v7, v7
	v_pk_mul_f32 v[24:25], v[22:23], v[24:25]
	v_fmamk_f32 v9, v10, 0xbfb8aa3b, v85
	v_add_f32_e32 v7, 1.0, v7
	v_rcp_f32_e32 v7, v7
	v_exp_f32_e32 v9, v9
	v_fmamk_f32 v11, v11, 0xbfb8aa3b, v85
	v_mul_f32_e32 v7, v92, v7
	v_exp_f32_e32 v23, v7
	v_fmamk_f32 v7, v27, 0xbfb8aa3b, v84
	v_exp_f32_e32 v7, v7
	v_fma_f32 v10, -v23, v23, 1.0
	v_add_f32_e32 v9, 1.0, v9
	v_add_f32_e32 v7, 1.0, v7
	v_rcp_f32_e32 v7, v7
	v_fmamk_f32 v12, v12, 0xbfb8aa3b, v85
	v_rcp_f32_e32 v9, v9
	v_sqrt_f32_e64 v10, |v10|
	v_mul_f32_e32 v7, v92, v7
	v_exp_f32_e32 v21, v7
	v_fmamk_f32 v7, v28, 0xbfb8aa3b, v84
	v_exp_f32_e32 v7, v7
	v_exp_f32_e32 v11, v11
	v_exp_f32_e32 v12, v12
	v_add_f32_e32 v7, 1.0, v7
	v_rcp_f32_e32 v7, v7
	v_mul_f32_e32 v10, v9, v10
	v_add_f32_e32 v9, 1.0, v11
	v_fma_f32 v11, -v21, v21, 1.0
	v_mul_f32_e32 v7, v92, v7
	v_exp_f32_e32 v7, v7
	v_add_f32_e32 v12, 1.0, v12
	v_rcp_f32_e32 v9, v9
	v_fma_f32 v19, -v7, v7, 1.0
	v_sqrt_f32_e64 v22, |v19|
	v_fmamk_f32 v19, v29, 0xbfb8aa3b, v84
	v_sqrt_f32_e64 v11, |v11|
	v_rcp_f32_e32 v12, v12
	v_exp_f32_e32 v26, v19
	v_mul_f32_e32 v19, v9, v11
	v_mul_f32_e32 v9, v12, v22
	v_mul_f32_e32 v27, v68, v9
	v_add_f32_e32 v9, 1.0, v26
	v_fmamk_f32 v12, v30, 0xbfb8aa3b, v84
	v_rcp_f32_e32 v9, v9
	v_exp_f32_e32 v12, v12
	v_fmamk_f32 v11, v13, 0xbfb8aa3b, v85
	v_mul_f32_e32 v9, v92, v9
	v_add_f32_e32 v12, 1.0, v12
	v_exp_f32_e32 v9, v9
	v_rcp_f32_e32 v12, v12
	v_fmamk_f32 v16, v16, 0xbfb8aa3b, v84
	v_fma_f32 v13, -v9, v9, 1.0
	v_mul_f32_e32 v12, v92, v12
	v_sqrt_f32_e64 v22, |v13|
	v_exp_f32_e32 v13, v12
	v_fmamk_f32 v12, v31, 0xbfb8aa3b, v84
	v_exp_f32_e32 v12, v12
	v_exp_f32_e32 v16, v16
	v_exp_f32_e32 v11, v11
	v_add_f32_e32 v12, 1.0, v12
	v_rcp_f32_e32 v12, v12
	v_add_f32_e32 v16, 1.0, v16
	v_rcp_f32_e32 v16, v16
	v_fmamk_f32 v15, v15, 0xbfb8aa3b, v85
	v_mul_f32_e32 v12, v92, v12
	v_exp_f32_e32 v29, v12
	v_fmamk_f32 v14, v14, 0xbfb8aa3b, v85
	v_exp_f32_e32 v15, v15
	v_mul_f32_e32 v16, v92, v16
	v_fma_f32 v26, -v13, v13, 1.0
	v_add_f32_e32 v11, 1.0, v11
	v_exp_f32_e32 v14, v14
	v_fmamk_f32 v0, v0, 0xbfb8aa3b, v85
	v_exp_f32_e32 v16, v16
	v_rcp_f32_e32 v11, v11
	v_sqrt_f32_e64 v12, |v26|
	v_fma_f32 v26, -v29, v29, 1.0
	v_add_f32_e32 v15, 1.0, v15
	v_fmamk_f32 v1, v1, 0xbfb8aa3b, v85
	v_exp_f32_e32 v0, v0
	v_rcp_f32_e32 v15, v15
	v_sqrt_f32_e64 v26, |v26|
	v_add_f32_e32 v14, 1.0, v14
	v_fmamk_f32 v2, v2, 0xbfb8aa3b, v85
	v_exp_f32_e32 v1, v1
	v_rcp_f32_e32 v14, v14
	v_mul_f32_e32 v30, v11, v22
	v_fma_f32 v22, -v16, v16, 1.0
	v_exp_f32_e32 v2, v2
	v_add_f32_e32 v0, 1.0, v0
	v_mul_f32_e32 v31, v15, v26
	v_fma_f32 v15, -v18, v18, 1.0
	v_rcp_f32_e32 v0, v0
	v_sqrt_f32_e64 v22, |v22|
	v_add_f32_e32 v1, 1.0, v1
	v_mul_f32_e32 v14, v14, v12
	v_fma_f32 v12, -v20, v20, 1.0
	v_rcp_f32_e32 v1, v1
	v_sqrt_f32_e64 v15, |v15|
	v_fmamk_f32 v3, v3, 0xbfb8aa3b, v85
	v_add_f32_e32 v2, 1.0, v2
	v_exp_f32_e32 v4, v4
	v_rcp_f32_e32 v2, v2
	v_sqrt_f32_e64 v12, |v12|
	v_mul_f32_e32 v0, v0, v22
	v_exp_f32_e32 v3, v3
	v_mul_f32_e32 v0, v76, v0
	v_mul_f32_e32 v1, v1, v15
	v_mul_f32_e32 v0, v18, v0
	v_fmac_f32_e32 v0, v77, v1
	v_fma_f32 v11, -v4, v4, 1.0
	v_mul_f32_e32 v2, v2, v12
	v_mul_f32_e32 v0, v20, v0
	v_add_f32_e32 v3, 1.0, v3
	v_fmac_f32_e32 v0, v80, v2
	v_mul_f32_e32 v17, v74, v17
	v_rcp_f32_e32 v3, v3
	v_sqrt_f32_e64 v11, |v11|
	v_mul_f32_e32 v15, v4, v0
	v_mul_f32_e32 v0, v111, v114
	v_mul_f32_e32 v1, v115, v116
	v_mov_b32_e32 v112, v71
	v_mov_b32_e32 v113, v70
	v_mul_f32_e32 v0, v0, v1
	v_mul_f32_e32 v1, v114, v17
	v_pk_mul_f32 v[24:25], v[112:113], v[24:25]
	v_fmac_f32_e32 v1, v75, v5
	v_mul_f32_e32 v1, v115, v1
	v_fmac_f32_e32 v24, v8, v25
	v_mul_f32_e32 v3, v3, v11
	v_fmac_f32_e32 v1, v82, v117
	v_mov_b32_e32 v22, v72
	v_mov_b32_e32 v11, v24
	v_mul_f32_e32 v2, v72, v10
	v_fmac_f32_e32 v15, v81, v3
	v_mul_f32_e32 v26, v116, v1
	v_pk_fma_f32 v[2:3], v[22:23], v[10:11], v[2:3] op_sel_hi:[1,1,0]
	v_mul_f32_e32 v1, v9, v27
	v_mov_b32_e32 v17, v73
	v_mov_b32_e32 v5, v3
	v_fmac_f32_e32 v1, v69, v30
	v_pk_mul_f32 v[10:11], v[16:17], v[18:19]
	v_pk_mul_f32 v[2:3], v[20:21], v[4:5]
	v_mov_b32_e32 v12, v23
	v_mov_b32_e32 v28, v21
	v_mul_f32_e32 v1, v13, v1
	v_pk_mul_f32 v[4:5], v[10:11], v[2:3]
	v_pk_fma_f32 v[10:11], v[16:17], v[18:19], v[2:3]
	v_pk_mul_f32 v[2:3], v[6:7], v[8:9]
	v_pk_mul_f32 v[6:7], v[12:13], v[28:29]
	v_fmac_f32_e32 v1, v78, v14
	v_pk_mul_f32 v[2:3], v[2:3], v[6:7]
	v_mul_f32_e32 v7, v29, v1
	v_fmac_f32_e32 v26, v83, v118
	v_fmac_f32_e32 v7, v79, v31
	ds_bpermute_b32 v14, v110, v4
	ds_bpermute_b32 v16, v110, v15
	ds_bpermute_b32 v12, v110, v0
	ds_bpermute_b32 v6, v110, v26
	ds_bpermute_b32 v1, v110, v2
	ds_bpermute_b32 v13, v110, v11
	ds_bpermute_b32 v8, v110, v3
	ds_bpermute_b32 v9, v110, v7
	s_and_saveexec_b64 s[46:47], s[42:43]
	s_cbranch_execz .LBB0_353
	v_fmac_f32_e32 v15, 0, v4
	s_waitcnt lgkmcnt(6)
	v_fmac_f32_e32 v16, v15, v14
	v_fmac_f32_e32 v26, v0, v16
	s_waitcnt lgkmcnt(4)
	v_fmac_f32_e32 v6, v26, v12
	v_mul_f32_e32 v15, v2, v6
	v_pk_mul_f32 v[4:5], v[4:5], v[14:15]
	v_pk_add_f32 v[10:11], v[10:11], v[14:15]
	s_waitcnt lgkmcnt(3)
	v_mov_b32_e32 v6, v1
	v_mov_b32_e32 v10, v4
	v_pk_mul_f32 v[4:5], v[0:1], v[4:5]
	s_waitcnt lgkmcnt(2)
	v_pk_fma_f32 v[10:11], v[0:1], v[10:11], v[12:13]
	v_pk_mul_f32 v[4:5], v[4:5], v[12:13]
	v_mov_b32_e32 v0, v1
	v_mov_b32_e32 v5, v11
	v_pk_mul_f32 v[10:11], v[2:3], v[4:5]
	v_pk_fma_f32 v[4:5], v[2:3], v[4:5], v[6:7]
	v_pk_mul_f32 v[0:1], v[10:11], v[0:1]
	s_waitcnt lgkmcnt(0)
	v_pk_mov_b32 v[2:3], v[2:3], v[8:9] op_sel:[1,0]
	v_mov_b32_e32 v4, v0
	v_pk_mul_f32 v[0:1], v[2:3], v[0:1]
	v_pk_fma_f32 v[2:3], v[2:3], v[4:5], v[8:9]
	v_pk_mul_f32 v[0:1], v[0:1], v[8:9]
	s_nop 0
	v_mov_b32_e32 v1, v3
	ds_write_b64 v97, v[0:1]
.LBB0_353:
	s_or_b64 exec, exec, s[46:47]
	s_waitcnt lgkmcnt(3)
	ds_read_b128 v[0:3], v109 offset:16384
	ds_read_b128 v[4:7], v109 offset:24576
	s_waitcnt lgkmcnt(1)
	v_mfma_f32_32x32x16_bf16 v[16:31], v[48:51], v[0:3], 0
	s_waitcnt lgkmcnt(0)
	v_mfma_f32_32x32x16_bf16 v[0:15], v[48:51], v[4:7], 0
	ds_read_b128 v[48:51], v109 offset:17408
	ds_read_b128 v[112:115], v109 offset:25600
	s_waitcnt lgkmcnt(1)
	v_mfma_f32_32x32x16_bf16 v[16:31], v[56:59], v[48:51], v[16:31]
	s_waitcnt lgkmcnt(0)
	v_mfma_f32_32x32x16_bf16 v[0:15], v[56:59], v[112:115], v[0:15]
	ds_read_b128 v[48:51], v109 offset:18432
	ds_read_b128 v[56:59], v109 offset:26624
	s_waitcnt lgkmcnt(1)
	v_mfma_f32_32x32x16_bf16 v[16:31], v[60:63], v[48:51], v[16:31]
	s_waitcnt lgkmcnt(0)
	v_mfma_f32_32x32x16_bf16 v[0:15], v[60:63], v[56:59], v[0:15]
	ds_read_b128 v[48:51], v109 offset:19456
	ds_read_b128 v[56:59], v109 offset:27648
	s_waitcnt lgkmcnt(1)
	v_mfma_f32_32x32x16_bf16 v[16:31], v[52:55], v[48:51], v[16:31]
	v_mov_b32_e32 v48, v77
	s_waitcnt lgkmcnt(0)
	v_mfma_f32_32x32x16_bf16 v[0:15], v[52:55], v[56:59], v[0:15]
	s_nop 8
	v_fmamk_f32 v17, v17, 0xbfb8aa3b, v86
	v_exp_f32_e32 v17, v17
	v_fmamk_f32 v16, v16, 0xbfb8aa3b, v86
	v_exp_f32_e32 v16, v16
	v_add_f32_e32 v17, 1.0, v17
	v_rcp_f32_e32 v17, v17
	v_fmamk_f32 v4, v4, 0xbfb8aa3b, v87
	v_exp_f32_e32 v4, v4
	v_mul_f32_e32 v17, v93, v17
	v_exp_f32_e32 v49, v17
	v_fmamk_f32 v17, v18, 0xbfb8aa3b, v86
	v_exp_f32_e32 v17, v17
	v_add_f32_e32 v4, 1.0, v4
	v_rcp_f32_e32 v4, v4
	v_fmamk_f32 v5, v5, 0xbfb8aa3b, v87
	v_add_f32_e32 v17, 1.0, v17
	v_rcp_f32_e32 v17, v17
	v_exp_f32_e32 v5, v5
	v_fmamk_f32 v8, v8, 0xbfb8aa3b, v87
	v_mul_f32_e32 v17, v93, v17
	v_exp_f32_e32 v18, v17
	v_fmamk_f32 v17, v19, 0xbfb8aa3b, v86
	v_exp_f32_e32 v17, v17
	v_add_f32_e32 v5, 1.0, v5
	v_exp_f32_e32 v8, v8
	v_add_f32_e32 v17, 1.0, v17
	v_rcp_f32_e32 v17, v17
	v_fmamk_f32 v6, v6, 0xbfb8aa3b, v87
	v_add_f32_e32 v8, 1.0, v8
	v_fmamk_f32 v7, v7, 0xbfb8aa3b, v87
	v_mul_f32_e32 v17, v93, v17
	v_exp_f32_e32 v50, v17
	v_fmamk_f32 v17, v20, 0xbfb8aa3b, v86
	v_exp_f32_e32 v17, v17
	v_exp_f32_e32 v6, v6
	v_add_f32_e32 v17, 1.0, v17
	v_rcp_f32_e32 v17, v17
	v_exp_f32_e32 v7, v7
	v_add_f32_e32 v6, 1.0, v6
	v_rcp_f32_e32 v6, v6
	v_mul_f32_e32 v17, v93, v17
	v_exp_f32_e32 v53, v17
	v_add_f32_e32 v7, 1.0, v7
	v_rcp_f32_e32 v7, v7
	v_fmamk_f32 v9, v9, 0xbfb8aa3b, v87
	v_fma_f32 v17, -v53, v53, 1.0
	v_sqrt_f32_e64 v17, |v17|
	v_exp_f32_e32 v9, v9
	v_fmamk_f32 v10, v10, 0xbfb8aa3b, v87
	v_mul_f32_e32 v55, v4, v17
	v_fmamk_f32 v4, v21, 0xbfb8aa3b, v86
	v_exp_f32_e32 v4, v4
	v_rcp_f32_e32 v17, v5
	v_rcp_f32_e32 v21, v8
	v_add_f32_e32 v9, 1.0, v9
	v_add_f32_e32 v4, 1.0, v4
	v_rcp_f32_e32 v4, v4
	v_rcp_f32_e32 v9, v9
	v_exp_f32_e32 v10, v10
	v_mul_f32_e32 v4, v93, v4
	v_exp_f32_e32 v5, v4
	v_add_f32_e32 v10, 1.0, v10
	v_rcp_f32_e32 v10, v10
	v_add_f32_e32 v16, 1.0, v16
	v_fma_f32 v4, -v5, v5, 1.0
	v_sqrt_f32_e64 v4, |v4|
	v_fmamk_f32 v3, v3, 0xbfb8aa3b, v87
	v_fmamk_f32 v2, v2, 0xbfb8aa3b, v87
	v_fmamk_f32 v1, v1, 0xbfb8aa3b, v87
	v_mul_f32_e32 v20, v17, v4
	v_fmamk_f32 v4, v22, 0xbfb8aa3b, v86
	v_exp_f32_e32 v4, v4
	v_rcp_f32_e32 v16, v16
	v_add_f32_e32 v4, 1.0, v4
	v_rcp_f32_e32 v4, v4
	v_exp_f32_e32 v3, v3
	v_exp_f32_e32 v2, v2
	v_mul_f32_e32 v4, v93, v4
	v_exp_f32_e32 v4, v4
	v_exp_f32_e32 v1, v1
	v_mul_f32_e32 v16, v93, v16
	v_fma_f32 v17, -v4, v4, 1.0
	v_sqrt_f32_e64 v22, |v17|
	v_fmamk_f32 v17, v23, 0xbfb8aa3b, v86
	v_exp_f32_e32 v17, v17
	v_add_f32_e32 v3, 1.0, v3
	v_add_f32_e32 v2, 1.0, v2
	v_add_f32_e32 v1, 1.0, v1
	v_add_f32_e32 v17, 1.0, v17
	v_rcp_f32_e32 v17, v17
	v_fmamk_f32 v0, v0, 0xbfb8aa3b, v87
	v_exp_f32_e32 v16, v16
	v_rcp_f32_e32 v3, v3
	v_mul_f32_e32 v17, v93, v17
	v_exp_f32_e32 v17, v17
	v_rcp_f32_e32 v2, v2
	v_rcp_f32_e32 v1, v1
	v_fma_f32 v19, -v17, v17, 1.0
	v_sqrt_f32_e64 v23, |v19|
	v_fmamk_f32 v19, v24, 0xbfb8aa3b, v86
	v_exp_f32_e32 v19, v19
	v_pk_mul_f32 v[6:7], v[6:7], v[22:23]
	v_exp_f32_e32 v0, v0
	v_pk_mul_f32 v[6:7], v[82:83], v[6:7]
	v_add_f32_e32 v19, 1.0, v19
	v_rcp_f32_e32 v19, v19
	v_add_f32_e32 v0, 1.0, v0
	v_rcp_f32_e32 v0, v0
	v_fmac_f32_e32 v6, v4, v7
	v_mul_f32_e32 v8, v93, v19
	v_exp_f32_e32 v8, v8
	s_nop 0
	v_fma_f32 v19, -v8, v8, 1.0
	v_sqrt_f32_e64 v19, |v19|
	s_nop 0
	v_mul_f32_e32 v22, v21, v19
	v_fmamk_f32 v19, v25, 0xbfb8aa3b, v86
	v_exp_f32_e32 v19, v19
	v_mov_b32_e32 v21, v6
	v_add_f32_e32 v19, 1.0, v19
	v_rcp_f32_e32 v19, v19
	s_nop 0
	v_mul_f32_e32 v19, v93, v19
	v_exp_f32_e32 v54, v19
	s_nop 0
	v_fma_f32 v19, -v54, v54, 1.0
	v_sqrt_f32_e64 v19, |v19|
	s_nop 0
	v_mul_f32_e32 v23, v9, v19
	v_fmamk_f32 v9, v26, 0xbfb8aa3b, v86
	v_exp_f32_e32 v9, v9
	v_mov_b32_e32 v19, v16
	v_add_f32_e32 v9, 1.0, v9
	v_rcp_f32_e32 v9, v9
	s_nop 0
	v_mul_f32_e32 v9, v93, v9
	v_exp_f32_e32 v52, v9
	s_nop 0
	v_fma_f32 v9, -v52, v52, 1.0
	v_sqrt_f32_e64 v9, |v9|
	s_nop 0
	v_mul_f32_e32 v24, v10, v9
	v_fmamk_f32 v9, v27, 0xbfb8aa3b, v86
	v_exp_f32_e32 v9, v9
	v_fmamk_f32 v10, v11, 0xbfb8aa3b, v87
	v_exp_f32_e32 v10, v10
	v_add_f32_e32 v9, 1.0, v9
	v_rcp_f32_e32 v9, v9
	v_add_f32_e32 v10, 1.0, v10
	v_rcp_f32_e32 v11, v10
	v_mul_f32_e32 v9, v93, v9
	v_exp_f32_e32 v10, v9
	s_nop 0
	v_fma_f32 v9, -v10, v10, 1.0
	v_sqrt_f32_e64 v9, |v9|
	s_nop 0
	v_mul_f32_e32 v9, v11, v9
	v_mul_f32_e32 v25, v73, v9
	v_fmamk_f32 v9, v28, 0xbfb8aa3b, v86
	v_exp_f32_e32 v9, v9
	v_fmamk_f32 v11, v12, 0xbfb8aa3b, v87
	v_exp_f32_e32 v11, v11
	v_add_f32_e32 v9, 1.0, v9
	v_rcp_f32_e32 v9, v9
	v_add_f32_e32 v11, 1.0, v11
	v_rcp_f32_e32 v11, v11
	v_mul_f32_e32 v9, v93, v9
	v_exp_f32_e32 v26, v9
	s_nop 0
	v_fma_f32 v9, -v26, v26, 1.0
	v_sqrt_f32_e64 v9, |v9|
	s_nop 0
	v_mul_f32_e32 v27, v11, v9
	v_fmamk_f32 v9, v29, 0xbfb8aa3b, v86
	v_exp_f32_e32 v9, v9
	v_fmamk_f32 v11, v13, 0xbfb8aa3b, v87
	v_exp_f32_e32 v11, v11
	v_add_f32_e32 v9, 1.0, v9
	v_rcp_f32_e32 v9, v9
	v_add_f32_e32 v11, 1.0, v11
	v_rcp_f32_e32 v11, v11
	v_mul_f32_e32 v9, v93, v9
	v_exp_f32_e32 v28, v9
	s_nop 0
	v_fma_f32 v9, -v28, v28, 1.0
	v_sqrt_f32_e64 v9, |v9|
	s_nop 0
	v_mul_f32_e32 v29, v11, v9
	v_fmamk_f32 v9, v30, 0xbfb8aa3b, v86
	v_exp_f32_e32 v9, v9
	v_fmamk_f32 v11, v14, 0xbfb8aa3b, v87
	v_exp_f32_e32 v11, v11
	v_add_f32_e32 v9, 1.0, v9
	v_rcp_f32_e32 v9, v9
	v_mov_b32_e32 v14, v49
	v_add_f32_e32 v11, 1.0, v11
	v_rcp_f32_e32 v11, v11
	v_mul_f32_e32 v9, v93, v9
	v_exp_f32_e32 v30, v9
	s_nop 0
	v_fma_f32 v9, -v30, v30, 1.0
	v_sqrt_f32_e64 v9, |v9|
	s_nop 0
	v_mul_f32_e32 v56, v11, v9
	v_fmamk_f32 v9, v31, 0xbfb8aa3b, v86
	v_exp_f32_e32 v9, v9
	v_fmamk_f32 v11, v15, 0xbfb8aa3b, v87
	v_exp_f32_e32 v11, v11
	v_add_f32_e32 v9, 1.0, v9
	v_rcp_f32_e32 v9, v9
	v_add_f32_e32 v11, 1.0, v11
	v_rcp_f32_e32 v11, v11
	v_mul_f32_e32 v9, v93, v9
	v_exp_f32_e32 v31, v9
	s_nop 0
	v_fma_f32 v9, -v31, v31, 1.0
	v_sqrt_f32_e64 v9, |v9|
	s_nop 0
	v_mul_f32_e32 v9, v11, v9
	v_mul_f32_e32 v57, v79, v9
	v_fma_f32 v9, -v50, v50, 1.0
	v_sqrt_f32_e64 v13, |v9|
	v_fma_f32 v9, -v18, v18, 1.0
	v_sqrt_f32_e64 v12, |v9|
	v_fma_f32 v9, -v49, v49, 1.0
	v_sqrt_f32_e64 v9, |v9|
	v_pk_mul_f32 v[2:3], v[2:3], v[12:13]
	v_mul_f32_e32 v12, v1, v9
	v_fma_f32 v1, -v16, v16, 1.0
	v_sqrt_f32_e64 v1, |v1|
	v_pk_mul_f32 v[2:3], v[80:81], v[2:3]
	v_mov_b32_e32 v9, v74
	v_fmac_f32_e32 v2, v18, v3
	v_mul_f32_e32 v15, v0, v1
	v_mov_b32_e32 v13, v2
	v_mul_f32_e32 v0, v77, v12
	v_pk_fma_f32 v[2:3], v[48:49], v[12:13], v[0:1] op_sel_hi:[1,1,0]
	v_mul_f32_e32 v0, v53, v5
	v_mul_f32_e32 v1, v4, v17
	v_mul_f32_e32 v1, v0, v1
	v_mov_b32_e32 v4, v75
	v_mul_f32_e32 v0, v75, v20
	v_pk_fma_f32 v[6:7], v[4:5], v[20:21], v[0:1] op_sel_hi:[1,1,0]
	v_mul_f32_e32 v0, v52, v25
	v_mov_b32_e32 v17, v76
	v_mov_b32_e32 v51, v3
	v_fmac_f32_e32 v0, v72, v24
	v_pk_mul_f32 v[4:5], v[16:17], v[14:15]
	v_pk_mul_f32 v[12:13], v[18:19], v[50:51]
	v_mov_b32_e32 v11, v7
	v_mul_f32_e32 v0, v54, v0
	v_pk_mul_f32 v[2:3], v[4:5], v[12:13]
	v_pk_fma_f32 v[4:5], v[16:17], v[14:15], v[12:13]
	v_pk_mul_f32 v[12:13], v[8:9], v[54:55]
	v_pk_mul_f32 v[10:11], v[52:53], v[10:11]
	v_fmac_f32_e32 v0, v71, v23
	v_pk_mul_f32 v[6:7], v[12:13], v[10:11]
	v_pk_fma_f32 v[10:11], v[8:9], v[54:55], v[10:11]
	v_mul_f32_e32 v12, v8, v0
	v_mul_f32_e32 v0, v26, v28
	v_mul_f32_e32 v8, v30, v31
	v_mul_f32_e32 v14, v0, v8
	v_mul_f32_e32 v0, v30, v57
	v_fmac_f32_e32 v0, v78, v56
	v_mul_f32_e32 v0, v28, v0
	v_fmac_f32_e32 v0, v69, v29
	v_mul_f32_e32 v15, v26, v0
	v_fmac_f32_e32 v12, v70, v22
	v_fmac_f32_e32 v15, v68, v27
	ds_bpermute_b32 v9, v110, v2
	ds_bpermute_b32 v13, v110, v5
	ds_bpermute_b32 v8, v110, v1
	ds_bpermute_b32 v17, v110, v11
	ds_bpermute_b32 v0, v110, v6
	ds_bpermute_b32 v18, v110, v12
	ds_bpermute_b32 v16, v110, v14
	ds_bpermute_b32 v19, v110, v15
	s_and_saveexec_b64 s[46:47], s[42:43]
	s_cbranch_execz .LBB0_355
	s_waitcnt lgkmcnt(0)
	v_fmac_f32_e32 v19, 0, v16
	v_fmac_f32_e32 v15, v19, v14
	v_fmac_f32_e32 v18, v15, v0
	v_fmac_f32_e32 v12, v6, v18
	v_mul_f32_e32 v15, v12, v8
	v_pk_mul_f32 v[18:19], v[14:15], v[16:17]
	v_pk_add_f32 v[14:15], v[14:15], v[16:17]
	v_pk_mul_f32 v[16:17], v[18:19], v[0:1]
	v_mov_b32_e32 v14, v18
	v_pk_mul_f32 v[6:7], v[6:7], v[16:17]
	v_pk_fma_f32 v[10:11], v[14:15], v[0:1], v[10:11]
	v_mov_b32_e32 v0, v1
	v_mov_b32_e32 v7, v11
	v_pk_mul_f32 v[10:11], v[6:7], v[8:9]
	v_mov_b32_e32 v12, v1
	v_pk_mul_f32 v[0:1], v[0:1], v[10:11]
	v_pk_fma_f32 v[6:7], v[6:7], v[8:9], v[12:13]
	v_pk_mov_b32 v[8:9], v[8:9], v[2:3] op_sel:[1,0]
	v_mov_b32_e32 v6, v0
	v_pk_mul_f32 v[0:1], v[0:1], v[8:9]
	s_nop 0
	v_pk_mul_f32 v[0:1], v[2:3], v[0:1]
	v_pk_fma_f32 v[2:3], v[6:7], v[8:9], v[4:5]
	s_nop 0
	v_mov_b32_e32 v1, v3
	ds_write_b64 v97, v[0:1] offset:512

.LBB0_593:
	s_or_b64 exec, exec, s[42:43]
	v_mul_f32_e32 v8, 0xbfb8aa3b, v8
	v_exp_f32_e32 v10, v8
	s_mov_b32 s1, 0x3f2aaaab
	s_mov_b32 s6, 0x3f317218
	s_mov_b32 s7, 0x7f800000
	v_add_f32_e32 v11, 1.0, v10
	v_frexp_mant_f32_e32 v13, v11
	v_cvt_f64_f32_e32 v[8:9], v11
	v_add_f32_e32 v12, -1.0, v11
	v_frexp_exp_i32_f64_e32 v8, v[8:9]
	v_cmp_gt_f32_e32 vcc, s1, v13
	v_sub_f32_e32 v14, v12, v11
	v_sub_f32_e32 v12, v10, v12
	v_subbrev_co_u32_e32 v8, vcc, 0, v8, vcc
	v_add_f32_e32 v14, 1.0, v14
	v_sub_u32_e32 v9, 0, v8
	v_add_f32_e32 v12, v12, v14
	v_ldexp_f32 v11, v11, v9
	v_ldexp_f32 v9, v12, v9
	v_add_f32_e32 v12, -1.0, v11
	v_add_f32_e32 v15, 1.0, v11
	v_add_f32_e32 v13, 1.0, v12
	v_add_f32_e32 v16, -1.0, v15
	v_sub_f32_e32 v13, v11, v13
	v_sub_f32_e32 v11, v11, v16
	v_add_f32_e32 v13, v9, v13
	v_add_f32_e32 v9, v9, v11
	v_add_f32_e32 v11, v15, v9
	v_rcp_f32_e32 v16, v11
	v_add_f32_e32 v14, v12, v13
	v_sub_f32_e32 v12, v14, v12
	v_sub_f32_e32 v12, v13, v12
	v_sub_f32_e32 v13, v11, v15
	v_sub_f32_e32 v9, v9, v13
	v_mul_f32_e32 v13, v14, v16
	v_mul_f32_e32 v15, v11, v13
	v_fma_f32 v17, v13, v11, -v15
	v_fmac_f32_e32 v17, v13, v9
	v_add_f32_e32 v18, v15, v17
	v_sub_f32_e32 v19, v14, v18
	v_sub_f32_e32 v14, v14, v19
	v_sub_f32_e32 v15, v18, v15
	v_sub_f32_e32 v14, v14, v18
	v_add_f32_e32 v12, v12, v14
	v_sub_f32_e32 v14, v15, v17
	v_add_f32_e32 v12, v14, v12
	v_add_f32_e32 v14, v19, v12
	v_mul_f32_e32 v15, v16, v14
	v_mul_f32_e32 v17, v11, v15
	v_fma_f32 v11, v15, v11, -v17
	v_fmac_f32_e32 v11, v15, v9
	v_sub_f32_e32 v9, v19, v14
	v_add_f32_e32 v9, v12, v9
	v_add_f32_e32 v12, v17, v11
	v_sub_f32_e32 v18, v14, v12
	v_sub_f32_e32 v14, v14, v18
	v_sub_f32_e32 v17, v12, v17
	v_sub_f32_e32 v12, v14, v12
	v_add_f32_e32 v9, v9, v12
	v_sub_f32_e32 v11, v17, v11
	v_cvt_f32_i32_e32 v8, v8
	v_add_f32_e32 v9, v11, v9
	v_add_f32_e32 v11, v13, v15
	v_add_f32_e32 v9, v18, v9
	v_sub_f32_e32 v12, v11, v13
	v_mul_f32_e32 v9, v16, v9
	v_sub_f32_e32 v12, v15, v12
	v_add_f32_e32 v9, v12, v9
	v_mul_f32_e32 v15, 0x3f317218, v8
	v_add_f32_e32 v12, v11, v9
	v_fma_f32 v16, v8, s6, -v15
	v_mul_f32_e32 v13, v12, v12
	v_fmac_f32_e32 v16, 0xb102e308, v8
	v_sub_f32_e32 v8, v12, v11
	v_fmamk_f32 v14, v13, 0x3e9b6dac, v179
	v_sub_f32_e32 v8, v9, v8
	v_add_f32_e32 v9, v15, v16
	v_fmaak_f32 v14, v13, v14, 0x3f2aaada
	v_sub_f32_e32 v11, v9, v15
	v_ldexp_f32 v15, v12, 1
	v_mul_f32_e32 v12, v12, v13
	v_mul_f32_e32 v12, v12, v14
	v_add_f32_e32 v13, v15, v12
	v_sub_f32_e32 v14, v13, v15
	v_ldexp_f32 v8, v8, 1
	v_sub_f32_e32 v12, v12, v14
	v_add_f32_e32 v8, v8, v12
	v_add_f32_e32 v12, v13, v8
	v_sub_f32_e32 v13, v12, v13
	v_sub_f32_e32 v8, v8, v13
	v_add_f32_e32 v13, v9, v12
	v_sub_f32_e32 v14, v13, v9
	v_sub_f32_e32 v15, v13, v14
	v_sub_f32_e32 v11, v16, v11
	v_sub_f32_e32 v9, v9, v15
	v_sub_f32_e32 v12, v12, v14
	v_add_f32_e32 v9, v12, v9
	v_add_f32_e32 v12, v11, v8
	v_sub_f32_e32 v14, v12, v11
	v_sub_f32_e32 v15, v12, v14
	v_sub_f32_e32 v11, v11, v15
	v_sub_f32_e32 v8, v8, v14
	v_add_f32_e32 v9, v12, v9
	v_add_f32_e32 v8, v8, v11
	v_add_f32_e32 v11, v13, v9
	v_sub_f32_e32 v12, v11, v13
	v_sub_f32_e32 v9, v9, v12
	v_add_f32_e32 v8, v8, v9
	v_mul_f32_e32 v7, 0xbfb8aa3b, v7
	v_add_f32_e32 v8, v11, v8
	v_cmp_neq_f32_e32 vcc, s7, v10
	v_exp_f32_e32 v7, v7
	s_mov_b32 s8, 0x33800000
	v_cndmask_b32_e32 v8, v182, v8, vcc
	v_cmp_ngt_f32_e32 vcc, -1.0, v10
	v_cmp_gt_u32_e64 s[42:43], 32, v3
	v_lshl_add_u64 v[72:73], s[44:45], 0, v[144:145]
	v_cndmask_b32_e32 v8, v183, v8, vcc
	v_cmp_neq_f32_e32 vcc, -1.0, v10
	s_mov_b32 s4, 0
	s_waitcnt lgkmcnt(0)
	v_cndmask_b32_e32 v8, v184, v8, vcc
	v_cmp_lt_f32_e64 vcc, |v10|, s8
	s_barrier
	s_nop 0
	v_cndmask_b32_e32 v8, v8, v10, vcc
	v_add_f32_e32 v10, 1.0, v7
	v_mul_f32_e32 v167, 0xc1000000, v8
	v_add_f32_e32 v8, -1.0, v10
	v_sub_f32_e32 v9, v8, v10
	v_add_f32_e32 v9, 1.0, v9
	v_sub_f32_e32 v8, v7, v8
	v_add_f32_e32 v11, v8, v9
	v_frexp_mant_f32_e32 v12, v10
	v_cvt_f64_f32_e32 v[8:9], v10
	v_frexp_exp_i32_f64_e32 v8, v[8:9]
	v_cmp_gt_f32_e32 vcc, s1, v12
	v_readlane_b32 s1, v242, 2
	s_nop 0
	v_subbrev_co_u32_e32 v8, vcc, 0, v8, vcc
	v_sub_u32_e32 v9, 0, v8
	v_ldexp_f32 v10, v10, v9
	v_ldexp_f32 v9, v11, v9
	v_add_f32_e32 v11, -1.0, v10
	v_add_f32_e32 v14, 1.0, v10
	v_add_f32_e32 v12, 1.0, v11
	v_add_f32_e32 v15, -1.0, v14
	v_sub_f32_e32 v12, v10, v12
	v_sub_f32_e32 v10, v10, v15
	v_add_f32_e32 v12, v9, v12
	v_add_f32_e32 v9, v9, v10
	v_add_f32_e32 v10, v14, v9
	v_rcp_f32_e32 v15, v10
	v_add_f32_e32 v13, v11, v12
	v_sub_f32_e32 v11, v13, v11
	v_sub_f32_e32 v11, v12, v11
	v_sub_f32_e32 v12, v10, v14
	v_sub_f32_e32 v9, v9, v12
	v_mul_f32_e32 v12, v13, v15
	v_mul_f32_e32 v14, v10, v12
	v_fma_f32 v16, v12, v10, -v14
	v_fmac_f32_e32 v16, v12, v9
	v_add_f32_e32 v17, v14, v16
	v_sub_f32_e32 v18, v13, v17
	v_sub_f32_e32 v13, v13, v18
	v_sub_f32_e32 v14, v17, v14
	v_sub_f32_e32 v13, v13, v17
	v_add_f32_e32 v11, v11, v13
	v_sub_f32_e32 v13, v14, v16
	v_add_f32_e32 v11, v13, v11
	v_add_f32_e32 v13, v18, v11
	v_mul_f32_e32 v14, v15, v13
	v_mul_f32_e32 v16, v10, v14
	v_fma_f32 v10, v14, v10, -v16
	v_fmac_f32_e32 v10, v14, v9
	v_sub_f32_e32 v9, v18, v13
	v_add_f32_e32 v9, v11, v9
	v_add_f32_e32 v11, v16, v10
	v_sub_f32_e32 v17, v13, v11
	v_sub_f32_e32 v13, v13, v17
	v_sub_f32_e32 v16, v11, v16
	v_sub_f32_e32 v11, v13, v11
	v_add_f32_e32 v9, v9, v11
	v_sub_f32_e32 v10, v16, v10
	v_cvt_f32_i32_e32 v8, v8
	v_add_f32_e32 v9, v10, v9
	v_add_f32_e32 v10, v12, v14
	v_add_f32_e32 v9, v17, v9
	v_sub_f32_e32 v11, v10, v12
	v_mul_f32_e32 v9, v15, v9
	v_sub_f32_e32 v11, v14, v11
	v_add_f32_e32 v9, v11, v9
	v_mul_f32_e32 v14, 0x3f317218, v8
	v_add_f32_e32 v11, v10, v9
	v_fma_f32 v15, v8, s6, -v14
	v_mul_f32_e32 v12, v11, v11
	v_fmac_f32_e32 v15, 0xb102e308, v8
	v_sub_f32_e32 v8, v11, v10
	v_fmamk_f32 v13, v12, 0x3e9b6dac, v179
	v_sub_f32_e32 v8, v9, v8
	v_add_f32_e32 v9, v14, v15
	v_fmaak_f32 v13, v12, v13, 0x3f2aaada
	v_sub_f32_e32 v10, v9, v14
	v_ldexp_f32 v14, v11, 1
	v_mul_f32_e32 v11, v11, v12
	v_mul_f32_e32 v11, v11, v13
	v_add_f32_e32 v12, v14, v11
	v_sub_f32_e32 v13, v12, v14
	v_ldexp_f32 v8, v8, 1
	v_sub_f32_e32 v11, v11, v13
	v_add_f32_e32 v8, v8, v11
	v_add_f32_e32 v11, v12, v8
	v_sub_f32_e32 v12, v11, v12
	v_sub_f32_e32 v8, v8, v12
	v_add_f32_e32 v12, v9, v11
	v_sub_f32_e32 v13, v12, v9
	v_sub_f32_e32 v14, v12, v13
	v_sub_f32_e32 v10, v15, v10
	v_sub_f32_e32 v9, v9, v14
	v_sub_f32_e32 v11, v11, v13
	v_add_f32_e32 v9, v11, v9
	v_add_f32_e32 v11, v10, v8
	v_sub_f32_e32 v13, v11, v10
	v_sub_f32_e32 v14, v11, v13
	v_sub_f32_e32 v10, v10, v14
	v_sub_f32_e32 v8, v8, v13
	v_add_f32_e32 v9, v11, v9
	v_add_f32_e32 v8, v8, v10
	v_add_f32_e32 v10, v12, v9
	v_sub_f32_e32 v11, v10, v12
	v_sub_f32_e32 v9, v9, v11
	v_add_f32_e32 v8, v8, v9
	v_add_f32_e32 v8, v10, v8
	v_cmp_neq_f32_e32 vcc, s7, v7
	v_lshlrev_b32_e32 v9, 2, v0
	v_and_b32_e32 v9, 60, v9
	v_cndmask_b32_e32 v8, v182, v8, vcc
	v_cmp_ngt_f32_e32 vcc, -1.0, v7
	v_lshlrev_b32_e32 v10, 2, v9
	v_readlane_b32 s6, v242, 3
	v_cndmask_b32_e32 v8, v183, v8, vcc
	v_cmp_neq_f32_e32 vcc, -1.0, v7
	v_add_u32_e32 v170, 0, v10
	v_lshlrev_b32_e32 v171, 1, v9
	v_cndmask_b32_e32 v8, v184, v8, vcc
	v_cmp_lt_f32_e64 vcc, |v7|, s8
	v_add_u32_e32 v9, s6, v10
	v_lshl_add_u32 v169, v158, 3, s1
	v_cndmask_b32_e32 v7, v8, v7, vcc
	v_mul_f32_e32 v168, 0xc1000000, v7
	v_ashrrev_i32_e32 v7, 7, v0
	v_lshlrev_b32_e32 v10, 5, v7
	v_or_b32_e32 v5, v10, v5
	s_movk_i32 s1, 0x90
	v_readlane_b32 s7, v242, 4
	v_mul_lo_u32 v5, v5, s1
	v_lshl_add_u32 v14, v158, 2, s6
	v_add_u32_e32 v172, s7, v171
	v_add_u32_e32 v12, s7, v5
	v_lshlrev_b32_e32 v15, 12, v4
	v_and_b32_e32 v0, 0x1fffff80, v0
	v_lshl_add_u64 v[4:5], s[58:59], 0, v[144:145]
	s_mov_b64 s[6:7], 0x11b80000
	v_lshrrev_b32_e32 v8, 5, v3
	v_lshl_add_u32 v173, v0, 3, v169
	v_lshl_add_u64 v[74:75], v[4:5], 0, s[6:7]
	v_or_b32_e32 v0, 3, v2
	s_movk_i32 s6, 0x110
	v_and_b32_e32 v11, -4, v2
	v_mul_lo_u32 v188, v0, s1
	v_mul_lo_u32 v4, v0, s6
	v_lshl_or_b32 v0, v8, 2, v10
	v_lshl_add_u32 v16, v3, 4, 0
	v_mul_lo_u32 v174, v11, s1
	v_mul_lo_u32 v3, v11, s6
	v_mul_lo_u32 v5, v0, s6
	v_mul_lo_u32 v189, v0, s1
	s_lshl_b32 s1, s5, 7
	v_readlane_b32 s6, v243, 22
	s_add_i32 s1, s1, s6
	v_add_u32_e32 v190, s1, v2
	s_ashr_i32 s1, s0, 31
	s_lshl_b64 s[6:7], s[0:1], 12
	s_add_u32 s6, s58, s6
	v_readlane_b32 s1, v243, 59
	v_lshlrev_b32_e32 v144, 2, v1
	s_addc_u32 s7, s59, s7
	s_add_i32 s1, s1, s5
	v_lshlrev_b32_e32 v13, 4, v8
	v_lshl_add_u64 v[0:1], s[6:7], 0, v[144:145]
	s_mov_b64 s[6:7], 0x162eec40
	s_lshl_b32 s1, s1, 7
	v_cmp_lt_i32_e64 s[44:45], 0, v7
	v_cmp_lt_i32_e64 s[46:47], 1, v7
	v_cmp_lt_i32_e64 s[48:49], 2, v7
	v_cmp_gt_i32_e64 s[50:51], 3, v7
	v_cmp_gt_i32_e64 s[52:53], 2, v7
	v_cmp_gt_i32_e64 s[54:55], 1, v7
	v_lshl_add_u64 v[76:77], v[0:1], 0, s[6:7]
	v_add3_u32 v144, v6, s1, -2
	v_add_u32_e32 v191, s1, v2
	v_add_u32_e32 v192, v9, v3
	v_add_u32_e32 v193, v9, v4
	v_add_u32_e32 v194, v12, v13
	v_add_u32_e32 v195, v14, v5
	v_add_u32_e32 v196, v16, v15
	s_mov_b32 s1, 0
	v_mul_f32_e32 v159, 0xbfb8aa3b, v159
	v_mul_f32_e32 v160, 0xbfb8aa3b, v160
	v_mul_f32_e32 v161, 0xbfb8aa3b, v161
	v_mul_f32_e32 v162, 0xbfb8aa3b, v162
	v_mul_f32_e32 v167, 0x3fb8aa3b, v167
	v_mul_f32_e32 v168, 0x3fb8aa3b, v168
	s_branch .LBB0_595

.LBB0_601:
	s_mul_i32 s5, s1, 0x4a40
	s_add_i32 s5, s5, 0
	v_add_u32_e32 v24, s5, v171
	v_add_u32_e32 v0, v24, v174
	v_add_u32_e32 v26, 0x8800, v0
	ds_read2_b64 v[0:3], v26 offset1:18
	ds_read_b128 v[4:7], v170 offset:32768
	ds_read_b128 v[8:11], v170 offset:33024
	ds_read_b128 v[12:15], v170 offset:33280
	ds_read_b128 v[16:19], v170 offset:33536
	ds_read2_b64 v[20:23], v26 offset0:36 offset1:72
	v_add_u32_e32 v24, v24, v188
	s_waitcnt lgkmcnt(5)
	v_lshlrev_b32_e32 v28, 16, v0
	v_and_b32_e32 v29, 0xffff0000, v0
	v_lshlrev_b32_e32 v30, 16, v1
	v_and_b32_e32 v31, 0xffff0000, v1
	v_lshlrev_b32_e32 v56, 16, v2
	v_and_b32_e32 v57, 0xffff0000, v2
	v_lshlrev_b32_e32 v58, 16, v3
	v_and_b32_e32 v59, 0xffff0000, v3
	ds_read_b128 v[0:3], v170 offset:33792
	ds_read_b64 v[24:25], v24 offset:34816
	s_waitcnt lgkmcnt(2)
	v_lshlrev_b32_e32 v60, 16, v20
	v_and_b32_e32 v61, 0xffff0000, v20
	v_lshlrev_b32_e32 v62, 16, v21
	v_and_b32_e32 v63, 0xffff0000, v21
	v_lshlrev_b32_e32 v68, 16, v22
	v_and_b32_e32 v69, 0xffff0000, v22
	v_lshlrev_b32_e32 v70, 16, v23
	v_and_b32_e32 v71, 0xffff0000, v23
	s_waitcnt lgkmcnt(1)
	v_pk_fma_f32 v[20:21], v[4:5], v[28:29], v[0:1]
	v_pk_fma_f32 v[22:23], v[6:7], v[30:31], v[2:3]
	v_pk_fma_f32 v[20:21], v[8:9], v[56:57], v[20:21]
	v_pk_fma_f32 v[22:23], v[10:11], v[58:59], v[22:23]
	s_waitcnt lgkmcnt(0)
	v_lshlrev_b32_e32 v64, 16, v24
	v_and_b32_e32 v65, 0xffff0000, v24
	v_lshlrev_b32_e32 v66, 16, v25
	v_and_b32_e32 v67, 0xffff0000, v25
	v_pk_fma_f32 v[20:21], v[12:13], v[60:61], v[20:21]
	v_pk_fma_f32 v[22:23], v[14:15], v[62:63], v[22:23]
	v_pk_fma_f32 v[20:21], v[16:17], v[64:65], v[20:21]
	v_pk_fma_f32 v[22:23], v[18:19], v[66:67], v[22:23]
	ds_read2_b64 v[24:27], v26 offset0:90 offset1:108
	ds_write_b128 v192, v[20:23]
	v_cvt_pk_bf16_f32 v20, v20, v21
	v_cvt_pk_bf16_f32 v21, v22, v23
	v_add_u32_e32 v28, v172, v174
	ds_write_b64 v28, v[20:21]
	v_pk_fma_f32 v[20:21], v[4:5], v[56:57], v[0:1]
	v_pk_fma_f32 v[22:23], v[6:7], v[58:59], v[2:3]
	v_pk_fma_f32 v[20:21], v[8:9], v[60:61], v[20:21]
	v_pk_fma_f32 v[22:23], v[10:11], v[62:63], v[22:23]
	v_pk_fma_f32 v[20:21], v[12:13], v[64:65], v[20:21]
	v_pk_fma_f32 v[22:23], v[14:15], v[66:67], v[22:23]
	v_pk_fma_f32 v[20:21], v[16:17], v[68:69], v[20:21]
	v_pk_fma_f32 v[22:23], v[18:19], v[70:71], v[22:23]
	ds_write_b128 v192, v[20:23] offset:272
	v_cvt_pk_bf16_f32 v20, v20, v21
	v_cvt_pk_bf16_f32 v21, v22, v23
	ds_write_b64 v28, v[20:21] offset:144
	v_pk_fma_f32 v[20:21], v[4:5], v[60:61], v[0:1]
	v_pk_fma_f32 v[22:23], v[6:7], v[62:63], v[2:3]
	v_pk_fma_f32 v[0:1], v[4:5], v[64:65], v[0:1]
	v_pk_fma_f32 v[2:3], v[6:7], v[66:67], v[2:3]
	s_waitcnt lgkmcnt(4)
	v_lshlrev_b32_e32 v80, 16, v24
	v_and_b32_e32 v81, 0xffff0000, v24
	v_lshlrev_b32_e32 v24, 16, v25
	v_and_b32_e32 v25, 0xffff0000, v25
	v_pk_fma_f32 v[22:23], v[10:11], v[66:67], v[22:23]
	v_pk_fma_f32 v[20:21], v[8:9], v[64:65], v[20:21]
	v_pk_fma_f32 v[2:3], v[10:11], v[70:71], v[2:3]
	v_pk_fma_f32 v[0:1], v[8:9], v[68:69], v[0:1]
	v_lshlrev_b32_e32 v82, 16, v26
	v_and_b32_e32 v83, 0xffff0000, v26
	v_lshlrev_b32_e32 v26, 16, v27
	v_and_b32_e32 v27, 0xffff0000, v27
	v_pk_fma_f32 v[20:21], v[12:13], v[68:69], v[20:21]
	v_pk_fma_f32 v[22:23], v[14:15], v[70:71], v[22:23]
	v_pk_fma_f32 v[0:1], v[12:13], v[80:81], v[0:1]
	v_pk_fma_f32 v[2:3], v[14:15], v[24:25], v[2:3]
	v_pk_fma_f32 v[22:23], v[18:19], v[24:25], v[22:23]
	v_pk_fma_f32 v[20:21], v[16:17], v[80:81], v[20:21]
	v_pk_fma_f32 v[2:3], v[18:19], v[26:27], v[2:3]
	v_pk_fma_f32 v[0:1], v[16:17], v[82:83], v[0:1]
	ds_write_b128 v192, v[20:23] offset:544
	v_cvt_pk_bf16_f32 v20, v20, v21
	v_cvt_pk_bf16_f32 v21, v22, v23
	ds_write_b64 v28, v[20:21] offset:288
	ds_write_b128 v193, v[0:3]
	v_cvt_pk_bf16_f32 v0, v0, v1
	v_cvt_pk_bf16_f32 v1, v2, v3
	v_add_u32_e32 v2, v172, v188
	ds_write_b64 v2, v[0:1]
	s_waitcnt lgkmcnt(0)
	s_barrier
	ds_read_b128 v[56:59], v194
	ds_read_b128 v[0:3], v196
	ds_read_b128 v[64:67], v194 offset:32
	ds_read_b128 v[60:63], v196 offset:1024
	s_waitcnt lgkmcnt(2)
	v_mfma_f32_32x32x16_bf16 v[16:31], v[56:59], v[0:3], 0
	ds_read_b128 v[0:3], v196 offset:8192
	ds_read_b128 v[68:71], v196 offset:9216
	v_add_u32_e32 v79, 0x800, v195
	s_waitcnt lgkmcnt(1)
	v_mfma_f32_32x32x16_bf16 v[0:15], v[56:59], v[0:3], 0
	v_mfma_f32_32x32x16_bf16 v[16:31], v[64:67], v[60:63], v[16:31]
	s_waitcnt lgkmcnt(0)
	v_mfma_f32_32x32x16_bf16 v[0:15], v[64:67], v[68:71], v[0:15]
	ds_read_b128 v[68:71], v194 offset:64
	ds_read_b128 v[80:83], v196 offset:2048
	ds_read_b128 v[60:63], v194 offset:96
	ds_read_b128 v[84:87], v196 offset:3072
	s_waitcnt lgkmcnt(2)
	v_mfma_f32_32x32x16_bf16 v[16:31], v[68:71], v[80:83], v[16:31]
	ds_read2_b32 v[100:101], v195 offset1:68
	ds_read_b128 v[80:83], v196 offset:10240
	ds_read2_b32 v[156:157], v195 offset0:136 offset1:204
	ds_read2_b32 v[96:97], v79 offset0:32 offset1:100
	ds_read_b128 v[88:91], v196 offset:11264
	ds_read2_b32 v[142:143], v79 offset0:168 offset1:236
	v_add_u32_e32 v79, 0x1000, v195
	ds_read2_b32 v[140:141], v79 offset0:64 offset1:132
	v_add_u32_e32 v79, 0x1200, v195
	ds_read2_b32 v[138:139], v79 offset0:72 offset1:140
	s_waitcnt lgkmcnt(8)
	v_mfma_f32_32x32x16_bf16 v[16:31], v[60:63], v[84:87], v[16:31]
	v_add_u32_e32 v79, 0x1800, v195
	ds_read2_b32 v[120:121], v79 offset0:96 offset1:164
	v_add_u32_e32 v79, 0x1a00, v195
	ds_read2_b32 v[104:105], v79 offset0:104 offset1:172
	v_xor_b32_e32 v79, 32, v180
	s_waitcnt lgkmcnt(2)
	v_mov_b32_e32 v102, v138
	s_nop 4
	v_fmamk_f32 v16, v16, 0xbfb8aa3b, v159
	v_mfma_f32_32x32x16_bf16 v[0:15], v[68:71], v[80:83], v[0:15]
	v_exp_f32_e32 v16, v16
	v_and_b32_e32 v80, 64, v180
	v_add_u32_e32 v80, 64, v80
	v_cmp_lt_i32_e32 vcc, v79, v80
	v_add_f32_e32 v16, 1.0, v16
	v_rcp_f32_e32 v16, v16
	v_mfma_f32_32x32x16_bf16 v[0:15], v[60:63], v[88:91], v[0:15]
	s_waitcnt lgkmcnt(0)
	v_mov_b32_e32 v114, v104
	v_mov_b32_e32 v118, v105
	v_mul_f32_e32 v16, v167, v16
	v_exp_f32_e32 v80, v16
	v_fmamk_f32 v16, v17, 0xbfb8aa3b, v159
	s_nop 3
	s_nop 1
	v_fmamk_f32 v0, v0, 0xbfb8aa3b, v160
	v_exp_f32_e32 v0, v0
	v_exp_f32_e32 v16, v16
	v_fma_f32 v17, -v80, v80, 1.0
	v_add_f32_e32 v0, 1.0, v0
	v_fmamk_f32 v1, v1, 0xbfb8aa3b, v160
	v_rcp_f32_e32 v0, v0
	v_sqrt_f32_e64 v17, |v17|
	v_add_f32_e32 v16, 1.0, v16
	v_exp_f32_e32 v1, v1
	v_rcp_f32_e32 v16, v16
	v_mul_f32_e32 v0, v0, v17
	v_mul_f32_e32 v199, v100, v0
	v_add_f32_e32 v0, 1.0, v1
	v_mul_f32_e32 v1, v167, v16
	v_exp_f32_e32 v82, v1
	v_fmamk_f32 v1, v18, 0xbfb8aa3b, v159
	v_exp_f32_e32 v1, v1
	v_fmamk_f32 v2, v2, 0xbfb8aa3b, v160
	v_exp_f32_e32 v2, v2
	v_add_f32_e32 v1, 1.0, v1
	v_rcp_f32_e32 v1, v1
	v_fma_f32 v16, -v82, v82, 1.0
	v_rcp_f32_e32 v0, v0
	v_mul_f32_e32 v1, v167, v1
	v_exp_f32_e32 v84, v1
	v_sqrt_f32_e64 v1, |v16|
	v_add_f32_e32 v2, 1.0, v2
	v_rcp_f32_e32 v2, v2
	v_fma_f32 v16, -v84, v84, 1.0
	v_sqrt_f32_e64 v16, |v16|
	v_mul_f32_e32 v0, v0, v1
	v_mul_f32_e32 v200, v101, v0
	v_fmamk_f32 v17, v19, 0xbfb8aa3b, v159
	v_mul_f32_e32 v0, v2, v16
	v_fmamk_f32 v2, v3, 0xbfb8aa3b, v160
	v_exp_f32_e32 v2, v2
	v_mul_f32_e32 v201, v156, v0
	v_exp_f32_e32 v17, v17
	v_add_f32_e32 v0, 1.0, v2
	v_fmamk_f32 v2, v20, 0xbfb8aa3b, v159
	v_exp_f32_e32 v2, v2
	v_add_f32_e32 v1, 1.0, v17
	v_rcp_f32_e32 v1, v1
	v_fmamk_f32 v3, v4, 0xbfb8aa3b, v160
	v_add_f32_e32 v2, 1.0, v2
	v_rcp_f32_e32 v2, v2
	v_mul_f32_e32 v1, v167, v1
	v_exp_f32_e32 v86, v1
	v_mul_f32_e32 v2, v167, v2
	v_exp_f32_e32 v88, v2
	v_fmamk_f32 v2, v21, 0xbfb8aa3b, v159
	v_exp_f32_e32 v2, v2
	v_fma_f32 v1, -v86, v86, 1.0
	v_add_f32_e32 v2, 1.0, v2
	v_rcp_f32_e32 v2, v2
	v_rcp_f32_e32 v0, v0
	v_sqrt_f32_e64 v1, |v1|
	v_exp_f32_e32 v3, v3
	v_mul_f32_e32 v2, v167, v2
	v_exp_f32_e32 v90, v2
	v_fmamk_f32 v2, v22, 0xbfb8aa3b, v159
	v_exp_f32_e32 v2, v2
	v_mul_f32_e32 v0, v0, v1
	v_add_f32_e32 v1, 1.0, v3
	v_fma_f32 v3, -v88, v88, 1.0
	v_fmamk_f32 v4, v5, 0xbfb8aa3b, v160
	v_add_f32_e32 v2, 1.0, v2
	v_rcp_f32_e32 v1, v1
	v_sqrt_f32_e64 v3, |v3|
	v_rcp_f32_e32 v2, v2
	v_exp_f32_e32 v4, v4
	v_mul_f32_e32 v202, v157, v0
	v_mul_f32_e32 v0, v1, v3
	v_fma_f32 v3, -v90, v90, 1.0
	v_mul_f32_e32 v2, v167, v2
	v_add_f32_e32 v1, 1.0, v4
	v_rcp_f32_e32 v1, v1
	v_exp_f32_e32 v89, v2
	v_sqrt_f32_e64 v2, |v3|
	v_mul_f32_e32 v203, v96, v0
	v_fmamk_f32 v4, v6, 0xbfb8aa3b, v160
	v_mul_f32_e32 v0, v1, v2
	v_fmamk_f32 v1, v23, 0xbfb8aa3b, v159
	v_exp_f32_e32 v1, v1
	v_exp_f32_e32 v4, v4
	v_fmamk_f32 v2, v7, 0xbfb8aa3b, v160
	v_add_f32_e32 v1, 1.0, v1
	v_rcp_f32_e32 v1, v1
	v_add_f32_e32 v3, 1.0, v4
	v_fma_f32 v4, -v89, v89, 1.0
	v_mul_f32_e32 v1, v167, v1
	v_exp_f32_e32 v91, v1
	v_fmamk_f32 v1, v24, 0xbfb8aa3b, v159
	v_exp_f32_e32 v1, v1
	v_rcp_f32_e32 v3, v3
	v_sqrt_f32_e64 v4, |v4|
	v_exp_f32_e32 v2, v2
	v_add_f32_e32 v1, 1.0, v1
	v_rcp_f32_e32 v1, v1
	v_mul_f32_e32 v204, v97, v0
	v_mul_f32_e32 v0, v3, v4
	v_mul_f32_e32 v205, v142, v0
	v_add_f32_e32 v0, 1.0, v2
	v_fma_f32 v2, -v91, v91, 1.0
	v_rcp_f32_e32 v0, v0
	v_sqrt_f32_e64 v2, |v2|
	v_mul_f32_e32 v1, v167, v1
	v_exp_f32_e32 v94, v1
	v_fmamk_f32 v1, v25, 0xbfb8aa3b, v159
	v_mul_f32_e32 v0, v0, v2
	v_exp_f32_e32 v2, v1
	v_fmamk_f32 v3, v8, 0xbfb8aa3b, v160
	v_exp_f32_e32 v3, v3
	v_add_f32_e32 v2, 1.0, v2
	v_rcp_f32_e32 v2, v2
	v_mul_f32_e32 v206, v143, v0
	v_add_f32_e32 v0, 1.0, v3
	v_fmamk_f32 v3, v9, 0xbfb8aa3b, v160
	v_mul_f32_e32 v2, v167, v2
	v_exp_f32_e32 v4, v3
	v_exp_f32_e32 v98, v2
	v_rcp_f32_e32 v1, v0
	v_fma_f32 v0, -v94, v94, 1.0
	v_sqrt_f32_e64 v3, |v0|
	v_add_f32_e32 v0, 1.0, v4
	v_fma_f32 v2, -v98, v98, 1.0
	v_fmamk_f32 v4, v26, 0xbfb8aa3b, v159
	v_rcp_f32_e32 v0, v0
	v_sqrt_f32_e64 v2, |v2|
	v_exp_f32_e32 v6, v4
	v_mov_b32_e32 v4, v141
	v_mov_b32_e32 v5, v140
	v_pk_mul_f32 v[0:1], v[0:1], v[2:3]
	v_add_f32_e32 v2, 1.0, v6
	v_rcp_f32_e32 v2, v2
	v_fmamk_f32 v3, v10, 0xbfb8aa3b, v160
	v_exp_f32_e32 v3, v3
	v_mul_f32_e32 v2, v167, v2
	v_exp_f32_e32 v103, v2
	v_fmamk_f32 v2, v27, 0xbfb8aa3b, v159
	v_exp_f32_e32 v2, v2
	v_pk_mul_f32 v[92:93], v[4:5], v[0:1]
	v_add_f32_e32 v0, 1.0, v3
	v_fma_f32 v1, -v103, v103, 1.0
	v_add_f32_e32 v2, 1.0, v2
	v_rcp_f32_e32 v2, v2
	v_fmamk_f32 v3, v11, 0xbfb8aa3b, v160
	v_mul_f32_e32 v2, v167, v2
	v_exp_f32_e32 v85, v2
	v_fmamk_f32 v2, v28, 0xbfb8aa3b, v159
	v_exp_f32_e32 v2, v2
	v_rcp_f32_e32 v0, v0
	v_sqrt_f32_e64 v1, |v1|
	v_exp_f32_e32 v3, v3
	v_add_f32_e32 v2, 1.0, v2
	v_rcp_f32_e32 v2, v2
	v_mul_f32_e32 v0, v0, v1
	v_add_f32_e32 v1, 1.0, v3
	v_fma_f32 v3, -v85, v85, 1.0
	v_fmamk_f32 v4, v12, 0xbfb8aa3b, v160
	v_mul_f32_e32 v2, v167, v2
	v_rcp_f32_e32 v1, v1
	v_sqrt_f32_e64 v3, |v3|
	v_exp_f32_e32 v4, v4
	v_exp_f32_e32 v95, v2
	v_fmamk_f32 v2, v29, 0xbfb8aa3b, v159
	v_exp_f32_e32 v2, v2
	v_mul_f32_e32 v83, v1, v3
	v_add_f32_e32 v1, 1.0, v4
	v_fmamk_f32 v4, v13, 0xbfb8aa3b, v160
	v_exp_f32_e32 v4, v4
	v_add_f32_e32 v2, 1.0, v2
	v_rcp_f32_e32 v6, v2
	v_rcp_f32_e32 v3, v1
	v_fma_f32 v1, -v95, v95, 1.0
	v_sqrt_f32_e64 v5, |v1|
	v_add_f32_e32 v1, 1.0, v4
	v_rcp_f32_e32 v2, v1
	v_mul_f32_e32 v1, v167, v6
	v_exp_f32_e32 v99, v1
	v_fmamk_f32 v1, v30, 0xbfb8aa3b, v159
	v_exp_f32_e32 v1, v1
	v_fmamk_f32 v6, v14, 0xbfb8aa3b, v160
	v_exp_f32_e32 v8, v6
	v_add_f32_e32 v1, 1.0, v1
	v_rcp_f32_e32 v1, v1
	v_fma_f32 v4, -v99, v99, 1.0
	v_sqrt_f32_e64 v4, |v4|
	v_mul_f32_e32 v1, v167, v1
	v_exp_f32_e32 v115, v1
	v_fmamk_f32 v1, v31, 0xbfb8aa3b, v159
	v_exp_f32_e32 v1, v1
	v_fma_f32 v9, -v115, v115, 1.0
	v_add_f32_e32 v8, 1.0, v8
	v_add_f32_e32 v1, 1.0, v1
	v_rcp_f32_e32 v1, v1
	v_fmamk_f32 v10, v15, 0xbfb8aa3b, v160
	v_rcp_f32_e32 v8, v8
	v_mul_f32_e32 v1, v167, v1
	v_exp_f32_e32 v119, v1
	v_sqrt_f32_e64 v1, |v9|
	v_exp_f32_e32 v10, v10
	v_mov_b32_e32 v6, v121
	v_mov_b32_e32 v7, v120
	v_pk_mul_f32 v[2:3], v[2:3], v[4:5]
	v_add_f32_e32 v9, 1.0, v10
	v_pk_mul_f32 v[106:107], v[6:7], v[2:3]
	v_mul_f32_e32 v2, v8, v1
	v_fma_f32 v1, v82, v199, v200
	v_fma_f32 v10, -v119, v119, 1.0
	v_fma_f32 v1, v84, v1, v201
	v_fma_f32 v207, v86, v1, v202
	v_fma_f32 v1, v90, v203, v204
	v_rcp_f32_e32 v9, v9
	v_sqrt_f32_e64 v10, |v10|
	v_fma_f32 v1, v89, v1, v205
	v_fma_f32 v208, v91, v1, v206
	v_fma_f32 v1, v98, v93, v92
	v_fma_f32 v3, v99, v107, v106
	v_pk_mul_f32 v[6:7], v[88:89], v[90:91]
	v_pk_mul_f32 v[112:113], v[102:103], v[0:1]
	v_pk_mul_f32 v[108:109], v[114:115], v[2:3]
	v_pk_mul_f32 v[122:123], v[6:7], v[6:7] op_sel:[0,1] op_sel_hi:[1,0]
	v_pk_fma_f32 v[6:7], v[102:103], v[0:1], v[112:113] op_sel_hi:[1,1,0]
	v_pk_fma_f32 v[0:1], v[114:115], v[2:3], v[108:109] op_sel_hi:[1,1,0]
	v_mul_f32_e32 v4, v9, v10
	v_mov_b32_e32 v5, v1
	v_pk_mul_f32 v[110:111], v[118:119], v[4:5]
	v_mov_b32_e32 v81, v139
	v_mov_b32_e32 v87, v7
	v_pk_fma_f32 v[0:1], v[118:119], v[4:5], v[110:111] op_sel:[0,0,1] op_sel_hi:[1,1,0]
	v_pk_mul_f32 v[116:117], v[80:81], v[82:83]
	v_pk_mul_f32 v[2:3], v[84:85], v[86:87]
	v_mov_b32_e32 v114, v103
	v_mov_b32_e32 v118, v85
	v_cndmask_b32_e32 v79, v180, v79, vcc
	v_pk_mul_f32 v[130:131], v[116:117], v[2:3]
	v_pk_mul_f32 v[2:3], v[94:95], v[98:99]
	v_pk_mul_f32 v[4:5], v[114:115], v[118:119]
	v_lshlrev_b32_e32 v79, 2, v79
	v_pk_fma_f32 v[128:129], v[84:85], v[86:87], v[116:117]
	v_pk_mul_f32 v[132:133], v[2:3], v[4:5]
	ds_bpermute_b32 v102, v79, v207
	ds_bpermute_b32 v126, v79, v122
	ds_bpermute_b32 v109, v79, v208
	ds_bpermute_b32 v125, v79, v0
	ds_bpermute_b32 v136, v79, v130
	ds_bpermute_b32 v127, v79, v129
	ds_bpermute_b32 v135, v79, v132
	ds_bpermute_b32 v124, v79, v133
	s_and_saveexec_b64 s[58:59], s[42:43]
	s_cbranch_execz .LBB0_603
	v_fma_f32 v2, 0, v130, v207
	s_waitcnt lgkmcnt(3)
	v_fma_f32 v2, v2, v136, v102
	v_fma_f32 v2, v122, v2, v208
	v_fma_f32 v2, v2, v126, v109
	v_mul_f32_e32 v137, v132, v2
	v_pk_mul_f32 v[2:3], v[130:131], v[136:137]
	v_pk_add_f32 v[4:5], v[128:129], v[136:137]
	v_mov_b32_e32 v134, v122
	v_mov_b32_e32 v4, v2
	v_pk_mul_f32 v[2:3], v[122:123], v[2:3]
	s_waitcnt lgkmcnt(1)
	v_pk_fma_f32 v[4:5], v[134:135], v[4:5], v[126:127]
	v_pk_mul_f32 v[2:3], v[2:3], v[126:127]
	v_pk_mov_b32 v[0:1], v[134:135], v[0:1] op_sel:[1,0]
	v_mov_b32_e32 v3, v5
	v_pk_mul_f32 v[4:5], v[132:133], v[2:3]
	s_nop 0
	v_pk_mul_f32 v[4:5], v[4:5], v[0:1]
	v_pk_fma_f32 v[0:1], v[132:133], v[2:3], v[0:1]
	s_waitcnt lgkmcnt(0)
	v_pk_mov_b32 v[2:3], v[132:133], v[124:125] op_sel:[1,0]
	v_mov_b32_e32 v0, v4
	v_pk_mul_f32 v[4:5], v[2:3], v[4:5]
	v_pk_fma_f32 v[0:1], v[2:3], v[0:1], v[124:125]
	v_pk_mul_f32 v[4:5], v[4:5], v[124:125]
	s_nop 0
	v_mov_b32_e32 v5, v1
	ds_write_b64 v173, v[4:5]
.LBB0_603:
	s_or_b64 exec, exec, s[58:59]
	ds_read_b128 v[0:3], v196 offset:16384
	ds_read_b128 v[4:7], v196 offset:24576
	s_waitcnt lgkmcnt(1)
	v_mfma_f32_32x32x16_bf16 v[16:31], v[56:59], v[0:3], 0
	s_waitcnt lgkmcnt(0)
	v_mfma_f32_32x32x16_bf16 v[0:15], v[56:59], v[4:7], 0
	ds_read_b128 v[56:59], v196 offset:17408
	ds_read_b128 v[210:213], v196 offset:25600
	s_waitcnt lgkmcnt(1)
	v_mfma_f32_32x32x16_bf16 v[16:31], v[64:67], v[56:59], v[16:31]
	s_waitcnt lgkmcnt(0)
	v_mfma_f32_32x32x16_bf16 v[0:15], v[64:67], v[210:213], v[0:15]
	ds_read_b128 v[56:59], v196 offset:18432
	ds_read_b128 v[64:67], v196 offset:26624
	s_waitcnt lgkmcnt(1)
	v_mfma_f32_32x32x16_bf16 v[16:31], v[68:71], v[56:59], v[16:31]
	s_waitcnt lgkmcnt(0)
	v_mfma_f32_32x32x16_bf16 v[0:15], v[68:71], v[64:67], v[0:15]
	ds_read_b128 v[56:59], v196 offset:19456
	ds_read_b128 v[64:67], v196 offset:27648
	s_waitcnt lgkmcnt(1)
	v_mfma_f32_32x32x16_bf16 v[16:31], v[60:63], v[56:59], v[16:31]
	s_waitcnt lgkmcnt(0)
	v_mfma_f32_32x32x16_bf16 v[0:15], v[60:63], v[64:67], v[0:15]
	s_nop 9
	v_fmamk_f32 v16, v16, 0xbfb8aa3b, v161
	v_exp_f32_e32 v16, v16
	s_nop 0
	v_add_f32_e32 v16, 1.0, v16
	v_fmamk_f32 v0, v0, 0xbfb8aa3b, v162
	v_exp_f32_e32 v0, v0
	v_rcp_f32_e32 v16, v16
	v_fmamk_f32 v1, v1, 0xbfb8aa3b, v162
	v_add_f32_e32 v0, 1.0, v0
	v_rcp_f32_e32 v56, v0
	v_mul_f32_e32 v0, v168, v16
	v_exp_f32_e32 v0, v0
	v_exp_f32_e32 v1, v1
	v_fmamk_f32 v2, v2, 0xbfb8aa3b, v162
	v_fma_f32 v16, -v0, v0, 1.0
	v_sqrt_f32_e64 v16, |v16|
	v_add_f32_e32 v1, 1.0, v1
	v_rcp_f32_e32 v1, v1
	v_exp_f32_e32 v2, v2
	v_mul_f32_e32 v61, v56, v16
	v_fmamk_f32 v16, v17, 0xbfb8aa3b, v161
	v_exp_f32_e32 v16, v16
	v_add_f32_e32 v2, 1.0, v2
	v_rcp_f32_e32 v56, v2
	v_fmamk_f32 v3, v3, 0xbfb8aa3b, v162
	v_add_f32_e32 v16, 1.0, v16
	v_rcp_f32_e32 v16, v16
	v_exp_f32_e32 v3, v3
	v_mul_f32_e32 v16, v168, v16
	v_exp_f32_e32 v17, v16
	v_add_f32_e32 v3, 1.0, v3
	v_rcp_f32_e32 v57, v3
	v_fmamk_f32 v3, v4, 0xbfb8aa3b, v162
	v_fma_f32 v16, -v17, v17, 1.0
	v_sqrt_f32_e64 v16, |v16|
	v_exp_f32_e32 v3, v3
	v_mov_b32_e32 v60, v17
	v_mul_f32_e32 v62, v1, v16
	v_fmamk_f32 v1, v18, 0xbfb8aa3b, v161
	v_exp_f32_e32 v1, v1
	v_add_f32_e32 v3, 1.0, v3
	v_rcp_f32_e32 v3, v3
	v_mov_b32_e32 v16, v101
	v_add_f32_e32 v1, 1.0, v1
	v_rcp_f32_e32 v1, v1
	s_nop 0
	v_mul_f32_e32 v1, v168, v1
	v_exp_f32_e32 v2, v1
	s_nop 0
	v_fma_f32 v1, -v2, v2, 1.0
	v_sqrt_f32_e64 v58, |v1|
	v_fmamk_f32 v1, v19, 0xbfb8aa3b, v161
	v_exp_f32_e32 v1, v1
	s_nop 0
	v_add_f32_e32 v1, 1.0, v1
	v_rcp_f32_e32 v1, v1
	s_nop 0
	v_mul_f32_e32 v1, v168, v1
	v_exp_f32_e32 v18, v1
	s_nop 0
	v_fma_f32 v1, -v18, v18, 1.0
	v_sqrt_f32_e64 v59, |v1|
	v_fmamk_f32 v1, v20, 0xbfb8aa3b, v161
	v_exp_f32_e32 v1, v1
	v_pk_mul_f32 v[56:57], v[56:57], v[58:59]
	v_add_f32_e32 v1, 1.0, v1
	v_rcp_f32_e32 v1, v1
	v_pk_mul_f32 v[56:57], v[156:157], v[56:57]
	v_mul_f32_e32 v1, v168, v1
	v_exp_f32_e32 v4, v1
	v_fma_f32 v63, v2, v57, v56
	v_fma_f32 v1, -v4, v4, 1.0
	v_sqrt_f32_e64 v1, |v1|
	s_nop 0
	v_mul_f32_e32 v59, v3, v1
	v_fmamk_f32 v1, v21, 0xbfb8aa3b, v161
	v_exp_f32_e32 v1, v1
	v_fmamk_f32 v3, v5, 0xbfb8aa3b, v162
	v_exp_f32_e32 v3, v3
	v_add_f32_e32 v1, 1.0, v1
	v_rcp_f32_e32 v1, v1
	v_add_f32_e32 v3, 1.0, v3
	v_rcp_f32_e32 v3, v3
	v_mul_f32_e32 v1, v168, v1
	v_exp_f32_e32 v20, v1
	s_nop 0
	v_fma_f32 v1, -v20, v20, 1.0
	v_sqrt_f32_e64 v1, |v1|
	s_nop 0
	v_mul_f32_e32 v64, v3, v1
	v_fmamk_f32 v1, v22, 0xbfb8aa3b, v161
	v_exp_f32_e32 v1, v1
	v_fmamk_f32 v3, v6, 0xbfb8aa3b, v162
	v_exp_f32_e32 v3, v3
	v_add_f32_e32 v1, 1.0, v1
	v_rcp_f32_e32 v1, v1
	v_add_f32_e32 v3, 1.0, v3
	v_rcp_f32_e32 v6, v3
	v_mul_f32_e32 v1, v168, v1
	v_exp_f32_e32 v5, v1
	v_fmamk_f32 v3, v7, 0xbfb8aa3b, v162
	v_exp_f32_e32 v3, v3
	v_fma_f32 v1, -v5, v5, 1.0
	v_sqrt_f32_e64 v22, |v1|
	v_fmamk_f32 v1, v23, 0xbfb8aa3b, v161
	v_exp_f32_e32 v1, v1
	v_add_f32_e32 v3, 1.0, v3
	v_rcp_f32_e32 v7, v3
	v_fmamk_f32 v3, v8, 0xbfb8aa3b, v162
	v_add_f32_e32 v1, 1.0, v1
	v_rcp_f32_e32 v1, v1
	v_exp_f32_e32 v3, v3
	v_mul_f32_e32 v1, v168, v1
	v_exp_f32_e32 v21, v1
	v_add_f32_e32 v3, 1.0, v3
	v_rcp_f32_e32 v3, v3
	v_fma_f32 v1, -v21, v21, 1.0
	v_sqrt_f32_e64 v23, |v1|
	v_fmamk_f32 v1, v24, 0xbfb8aa3b, v161
	v_exp_f32_e32 v1, v1
	v_pk_mul_f32 v[6:7], v[6:7], v[22:23]
	v_add_f32_e32 v1, 1.0, v1
	v_rcp_f32_e32 v1, v1
	v_pk_mul_f32 v[6:7], v[142:143], v[6:7]
	v_mul_f32_e32 v1, v168, v1
	v_exp_f32_e32 v8, v1
	v_fma_f32 v65, v5, v7, v6
	v_fma_f32 v1, -v8, v8, 1.0
	v_sqrt_f32_e64 v1, |v1|
	s_nop 0
	v_mul_f32_e32 v1, v3, v1
	v_mul_f32_e32 v81, v140, v1
	v_fmamk_f32 v1, v25, 0xbfb8aa3b, v161
	v_exp_f32_e32 v1, v1
	v_fmamk_f32 v3, v9, 0xbfb8aa3b, v162
	v_exp_f32_e32 v3, v3
	v_add_f32_e32 v1, 1.0, v1
	v_rcp_f32_e32 v1, v1
	v_mov_b32_e32 v9, v96
	v_add_f32_e32 v3, 1.0, v3
	v_rcp_f32_e32 v3, v3
	v_mul_f32_e32 v1, v168, v1
	v_exp_f32_e32 v58, v1
	s_nop 0
	v_fma_f32 v1, -v58, v58, 1.0
	v_sqrt_f32_e64 v1, |v1|
	s_nop 0
	v_mul_f32_e32 v1, v3, v1
	v_mul_f32_e32 v83, v141, v1
	v_fmamk_f32 v1, v26, 0xbfb8aa3b, v161
	v_exp_f32_e32 v1, v1
	v_fmamk_f32 v3, v10, 0xbfb8aa3b, v162
	v_exp_f32_e32 v3, v3
	v_add_f32_e32 v1, 1.0, v1
	v_rcp_f32_e32 v1, v1
	v_add_f32_e32 v3, 1.0, v3
	v_rcp_f32_e32 v3, v3
	v_mul_f32_e32 v1, v168, v1
	v_exp_f32_e32 v10, v1
	s_nop 0
	v_fma_f32 v1, -v10, v10, 1.0
	v_sqrt_f32_e64 v1, |v1|
	s_nop 0
	v_mul_f32_e32 v1, v3, v1
	v_mul_f32_e32 v87, v138, v1
	v_fmamk_f32 v1, v27, 0xbfb8aa3b, v161
	v_exp_f32_e32 v1, v1
	v_fmamk_f32 v3, v11, 0xbfb8aa3b, v162
	v_exp_f32_e32 v3, v3
	v_add_f32_e32 v1, 1.0, v1
	v_rcp_f32_e32 v1, v1
	v_pk_mul_f32 v[26:27], v[4:5], v[20:21]
	v_add_f32_e32 v3, 1.0, v3
	v_rcp_f32_e32 v3, v3
	v_mul_f32_e32 v1, v168, v1
	v_exp_f32_e32 v22, v1
	v_mov_b32_e32 v11, v4
	v_fma_f32 v1, -v22, v22, 1.0
	v_sqrt_f32_e64 v1, |v1|
	s_nop 0
	v_mul_f32_e32 v1, v3, v1
	v_mul_f32_e32 v111, v139, v1
	v_fmamk_f32 v1, v28, 0xbfb8aa3b, v161
	v_exp_f32_e32 v1, v1
	v_fmamk_f32 v3, v12, 0xbfb8aa3b, v162
	v_exp_f32_e32 v3, v3
	v_add_f32_e32 v1, 1.0, v1
	v_rcp_f32_e32 v1, v1
	v_mov_b32_e32 v28, v97
	v_add_f32_e32 v3, 1.0, v3
	v_rcp_f32_e32 v3, v3
	v_mul_f32_e32 v1, v168, v1
	v_exp_f32_e32 v12, v1
	s_nop 0
	v_fma_f32 v1, -v12, v12, 1.0
	v_sqrt_f32_e64 v1, |v1|
	s_nop 0
	v_mul_f32_e32 v1, v3, v1
	v_mul_f32_e32 v113, v120, v1
	v_fmamk_f32 v1, v29, 0xbfb8aa3b, v161
	v_exp_f32_e32 v1, v1
	v_fmamk_f32 v3, v13, 0xbfb8aa3b, v162
	v_exp_f32_e32 v3, v3
	v_add_f32_e32 v1, 1.0, v1
	v_rcp_f32_e32 v1, v1
	v_mov_b32_e32 v29, v20
	v_add_f32_e32 v3, 1.0, v3
	v_rcp_f32_e32 v3, v3
	v_mul_f32_e32 v1, v168, v1
	v_exp_f32_e32 v24, v1
	s_nop 0
	v_fma_f32 v1, -v24, v24, 1.0
	v_sqrt_f32_e64 v1, |v1|
	s_nop 0
	v_mul_f32_e32 v1, v3, v1
	v_mul_f32_e32 v114, v121, v1
	v_fmamk_f32 v1, v30, 0xbfb8aa3b, v161
	v_exp_f32_e32 v1, v1
	v_fmamk_f32 v3, v14, 0xbfb8aa3b, v162
	v_exp_f32_e32 v3, v3
	v_add_f32_e32 v1, 1.0, v1
	v_rcp_f32_e32 v1, v1
	v_add_f32_e32 v3, 1.0, v3
	v_rcp_f32_e32 v3, v3
	v_mul_f32_e32 v1, v168, v1
	v_exp_f32_e32 v13, v1
	s_nop 0
	v_fma_f32 v1, -v13, v13, 1.0
	v_sqrt_f32_e64 v1, |v1|
	s_nop 0
	v_mul_f32_e32 v1, v3, v1
	v_mul_f32_e32 v116, v104, v1
	v_fmamk_f32 v1, v31, 0xbfb8aa3b, v161
	v_exp_f32_e32 v1, v1
	v_fmamk_f32 v3, v15, 0xbfb8aa3b, v162
	v_exp_f32_e32 v3, v3
	v_add_f32_e32 v1, 1.0, v1
	v_rcp_f32_e32 v1, v1
	v_pk_mul_f32 v[14:15], v[16:17], v[62:63]
	v_add_f32_e32 v3, 1.0, v3
	v_rcp_f32_e32 v3, v3
	v_mul_f32_e32 v1, v168, v1
	v_exp_f32_e32 v25, v1
	v_pk_fma_f32 v[30:31], v[16:17], v[62:63], v[14:15] op_sel_hi:[1,1,0]
	v_pk_mul_f32 v[62:63], v[26:27], v[26:27] op_sel:[0,1] op_sel_hi:[1,0]
	v_pk_mul_f32 v[26:27], v[28:29], v[64:65]
	v_fma_f32 v1, -v25, v25, 1.0
	v_sqrt_f32_e64 v1, |v1|
	v_pk_fma_f32 v[66:67], v[28:29], v[64:65], v[26:27] op_sel_hi:[1,1,0]
	v_pk_mul_f32 v[28:29], v[12:13], v[24:25]
	v_mov_b32_e32 v19, v31
	v_mul_f32_e32 v1, v3, v1
	v_mul_f32_e32 v118, v105, v1
	v_fma_f32 v1, v10, v111, v87
	v_fma_f32 v1, v58, v1, v83
	v_fma_f32 v16, v8, v1, v81
	v_fma_f32 v1, v13, v118, v116
	v_fma_f32 v1, v24, v1, v114
	v_fma_f32 v15, v12, v1, v113
	v_mov_b32_e32 v1, v100
	v_mov_b32_e32 v3, v0
	v_pk_mul_f32 v[64:65], v[28:29], v[28:29] op_sel:[0,1] op_sel_hi:[1,0]
	v_pk_mul_f32 v[28:29], v[0:1], v[60:61]
	v_pk_mul_f32 v[30:31], v[2:3], v[18:19]
	v_mov_b32_e32 v23, v67
	v_pk_mul_f32 v[70:71], v[28:29], v[30:31]
	v_pk_mul_f32 v[30:31], v[8:9], v[58:59]
	v_pk_mul_f32 v[60:61], v[10:11], v[22:23]
	v_pk_fma_f32 v[120:121], v[2:3], v[18:19], v[28:29]
	v_pk_mul_f32 v[96:97], v[30:31], v[60:61]
	v_pk_fma_f32 v[100:101], v[10:11], v[22:23], v[30:31]
	ds_bpermute_b32 v68, v79, v62
	ds_bpermute_b32 v27, v79, v16
	ds_bpermute_b32 v66, v79, v64
	ds_bpermute_b32 v69, v79, v70
	ds_bpermute_b32 v61, v79, v121
	ds_bpermute_b32 v67, v79, v101
	ds_bpermute_b32 v104, v79, v96
	ds_bpermute_b32 v1, v79, v15
	s_and_saveexec_b64 s[58:59], s[42:43]
	s_cbranch_execz .LBB0_605
	s_waitcnt lgkmcnt(0)
	v_fma_f32 v3, 0, v66, v1
	v_fma_f32 v3, v3, v64, v15
	v_fma_f32 v3, v3, v104, v27
	v_fma_f32 v3, v96, v3, v16
	v_mul_f32_e32 v139, v3, v68
	v_mov_b32_e32 v138, v64
	v_pk_mul_f32 v[140:141], v[64:65], v[66:67]
	v_pk_add_f32 v[138:139], v[138:139], v[66:67]
	v_mov_b32_e32 v105, v62
	v_mov_b32_e32 v138, v140
	v_pk_mul_f32 v[140:141], v[140:141], v[104:105]
	v_pk_fma_f32 v[138:139], v[138:139], v[104:105], v[100:101]
	v_pk_mul_f32 v[140:141], v[96:97], v[140:141]
	v_mov_b32_e32 v60, v62
	v_mov_b32_e32 v141, v139
	v_pk_mul_f32 v[138:139], v[140:141], v[68:69]
	v_pk_fma_f32 v[140:141], v[140:141], v[68:69], v[60:61]
	v_pk_mul_f32 v[138:139], v[62:63], v[138:139]
	v_pk_mov_b32 v[142:143], v[68:69], v[70:71] op_sel:[1,0]
	v_mov_b32_e32 v140, v138
	v_pk_mul_f32 v[138:139], v[138:139], v[142:143]
	v_pk_fma_f32 v[120:121], v[140:141], v[142:143], v[120:121]
	v_pk_mul_f32 v[138:139], v[70:71], v[138:139]
	s_nop 0
	v_mov_b32_e32 v139, v121
	ds_write_b64 v173, v[138:139] offset:512
